# res epilogue: LDS lane transpose for coalesced residual loads/stores + gray-code MFMA operand order in K-loops
# speedup vs baseline: 1.0088x; 1.0088x over previous
; #define PG8_STAGE(bufoff, gbase, voff) do { _Pragma("unroll") for (int _i = 0; _i < 2; ++_i) \
;         __builtin_amdgcn_global_load_lds((const unsigned*)((const char*)(gbase) + (voff)[_i]), (PG8_LAS unsigned*)(lds + (bufoff) + ldsw + _i * 8192), 16, 0, 0); } while (0)
; #define PG8_LDA(dst, b, h) do { _Pragma("unroll") for (int m = 0; m < 4; ++m) _Pragma("unroll") for (int k = 0; k < 2; ++k) dst[m][k] = *(const PG8_LAS bf16x8*)(lds + PG8_SA(b, h) + aoff + m * 2048 + k * 1024); } while (0)
; #define PG8_LDB(dst, b, h) do { _Pragma("unroll") for (int n = 0; n < 2; ++n) _Pragma("unroll") for (int k = 0; k < 2; ++k) dst[n][k] = *(const PG8_LAS bf16x8*)(lds + PG8_SB(b, h) + boff + n * 2048 + k * 1024); } while (0)
; #define PG8_MMA(ai, bj, At, Bt) do { __builtin_amdgcn_s_setprio(1); _Pragma("unroll") for (int m = 0; m < 4; ++m) _Pragma("unroll") for (int n = 0; n < 2; ++n) _Pragma("unroll") for (int k = 0; k < 2; ++k) \
;         acc[ai][bj][m][n] = __builtin_amdgcn_mfma_f32_16x16x32_bf16(Bt[n][k], At[m][k], acc[ai][bj][m][n], 0, 0, 0); __builtin_amdgcn_s_setprio(0); } while (0)
; #define PG8_WAIT_V(n) asm volatile("s_waitcnt vmcnt(" #n ")" ::: "memory")
; #define PG8_WAIT_L(n) asm volatile("s_waitcnt lgkmcnt(" #n ")" ::: "memory")
; #define PG8_BAR __builtin_amdgcn_s_barrier()
; #define PG8_SCHED __builtin_amdgcn_sched_barrier(0)
; template <class Epi, class Sched, bool ALIGN_EPI = false, bool SP2 = false>
; __device__ __forceinline__ void gemm_phase(PG8_LAS unsigned char* lds, const Gemm g, const Sched& S, const Epi& E) {
;     ...
;             const bool last = (t == nt - 2);
;             const char* a1 = cA + (size_t)(t + 1) * kstep;
;             const char* a2 = last ? nA : cA + (size_t)(t + 2) * kstep; const char* b2 = last ? nB : cB + (size_t)(t + 2) * kstep;
;             const char* a3 = a2 + kstep; const char* b3 = b2 + kstep;
;             if (last && has_next) S.a_ready(nxt);
;             if constexpr (SP2) {
;             PG8_LDB(B0, 0, 0); PG8_LDB(B1, 0, 1); PG8_SCHED; PG8_LDA(At, 0, 0); PG8_STAGE(PG8_SA(1, 1), a1 + hstep, voffA);
;             PG8_WAIT_V(8); PG8_WAIT_L(0); PG8_BAR; PG8_MMA(0, 0, At, B0); PG8_MMA(0, 1, At, B1); PG8_BAR; PG8_SCHED;
;             PG8_LDA(At, 0, 1); PG8_STAGE(PG8_SB(0, 0), b2, voffB); PG8_STAGE(PG8_SB(0, 1), b2 + hstep, voffB); PG8_STAGE(PG8_SA(0, 0), a2, voffA);
.LBB0_236:
	s_add_u32 s76, s86, 0xfffc0080
	s_addc_u32 s77, s87, -1
	s_add_i32 s80, 0, 0x10000
	s_cmp_eq_u32 s75, 12
	s_cselect_b32 s91, s66, s77
	s_cselect_b32 s90, s67, s76
	s_cselect_b32 s89, s39, s71
	s_cselect_b32 s88, s68, s69
	s_add_i32 s81, 0, 0x14000
	v_add_u32_e32 v154, s80, v176
	v_add_u32_e32 v186, s81, v176
	ds_read_b128 v[48:51], v154
	ds_read_b128 v[60:63], v154 offset:1024
	ds_read_b128 v[138:141], v154 offset:2048
	ds_read_b128 v[154:157], v154 offset:3072
	ds_read_b128 v[158:161], v186
	ds_read_b128 v[178:181], v186 offset:1024
	ds_read_b128 v[182:185], v186 offset:2048
	ds_read_b128 v[186:189], v186 offset:3072
	v_lshl_add_u64 v[194:195], s[86:87], 0, v[150:151]
	s_add_i32 m0, s15, 0xc000
	ds_read_b128 v[190:193], v177
	ds_read_b128 v[212:215], v177 offset:1024
	ds_read_b128 v[216:219], v177 offset:2048
	ds_read_b128 v[220:223], v177 offset:3072
	ds_read_b128 v[224:227], v177 offset:4096
	ds_read_b128 v[228:231], v177 offset:5120
	ds_read_b128 v[232:235], v177 offset:6144
	ds_read_b128 v[236:239], v177 offset:7168
	global_load_lds_dwordx4 v[194:195], off
	v_lshl_add_u64 v[194:195], s[86:87], 0, v[152:153]
	s_add_i32 m0, s15, 0xe000
	s_nop 0
	global_load_lds_dwordx4 v[194:195], off
	s_waitcnt vmcnt(8)
	s_waitcnt lgkmcnt(0)
	s_barrier
	s_setprio 1
	s_waitcnt lgkmcnt(0)
	v_mfma_f32_16x16x32_bf16 v[134:137], v[48:51], v[190:193], v[134:137]
	v_mfma_f32_16x16x32_bf16 v[126:129], v[138:141], v[190:193], v[126:129]
	v_mfma_f32_16x16x32_bf16 v[110:113], v[138:141], v[216:219], v[110:113]
	v_mfma_f32_16x16x32_bf16 v[118:121], v[48:51], v[216:219], v[118:121]
	v_mfma_f32_16x16x32_bf16 v[102:105], v[48:51], v[224:227], v[102:105]
	v_mfma_f32_16x16x32_bf16 v[94:97], v[138:141], v[224:227], v[94:97]
	v_mfma_f32_16x16x32_bf16 v[76:79], v[138:141], v[232:235], v[76:79]
	v_mfma_f32_16x16x32_bf16 v[86:89], v[48:51], v[232:235], v[86:89]
	v_mfma_f32_16x16x32_bf16 v[134:137], v[60:63], v[212:215], v[134:137]
	v_mfma_f32_16x16x32_bf16 v[126:129], v[154:157], v[212:215], v[126:129]
	v_mfma_f32_16x16x32_bf16 v[110:113], v[154:157], v[220:223], v[110:113]
	v_mfma_f32_16x16x32_bf16 v[118:121], v[60:63], v[220:223], v[118:121]
	v_mfma_f32_16x16x32_bf16 v[102:105], v[60:63], v[228:231], v[102:105]
	v_mfma_f32_16x16x32_bf16 v[94:97], v[154:157], v[228:231], v[94:97]
	v_mfma_f32_16x16x32_bf16 v[76:79], v[154:157], v[236:239], v[76:79]
	v_mfma_f32_16x16x32_bf16 v[86:89], v[60:63], v[236:239], v[86:89]
	s_setprio 0
	s_setprio 1
	v_mfma_f32_16x16x32_bf16 v[130:133], v[158:161], v[190:193], v[130:133]
	v_mfma_f32_16x16x32_bf16 v[122:125], v[182:185], v[190:193], v[122:125]
	v_mfma_f32_16x16x32_bf16 v[106:109], v[182:185], v[216:219], v[106:109]
	v_mfma_f32_16x16x32_bf16 v[114:117], v[158:161], v[216:219], v[114:117]
	v_mfma_f32_16x16x32_bf16 v[98:101], v[158:161], v[224:227], v[98:101]
	v_mfma_f32_16x16x32_bf16 v[90:93], v[182:185], v[224:227], v[90:93]
	v_mfma_f32_16x16x32_bf16 v[72:75], v[182:185], v[232:235], v[72:75]
	v_mfma_f32_16x16x32_bf16 v[82:85], v[158:161], v[232:235], v[82:85]
	v_mfma_f32_16x16x32_bf16 v[130:133], v[178:181], v[212:215], v[130:133]
	v_mfma_f32_16x16x32_bf16 v[122:125], v[186:189], v[212:215], v[122:125]
	v_mfma_f32_16x16x32_bf16 v[106:109], v[186:189], v[220:223], v[106:109]
	v_mfma_f32_16x16x32_bf16 v[114:117], v[178:181], v[220:223], v[114:117]
	v_mfma_f32_16x16x32_bf16 v[98:101], v[178:181], v[228:231], v[98:101]
	v_mfma_f32_16x16x32_bf16 v[90:93], v[186:189], v[228:231], v[90:93]
	v_mfma_f32_16x16x32_bf16 v[72:75], v[186:189], v[236:239], v[72:75]
	v_mfma_f32_16x16x32_bf16 v[82:85], v[178:181], v[236:239], v[82:85]
	s_setprio 0
	s_barrier
	s_add_i32 s76, s80, s13
	v_lshl_add_u64 v[194:195], s[88:89], 0, v[144:145]
	s_mov_b32 m0, s76
	ds_read_b128 v[190:193], v177 offset:16384
	ds_read_b128 v[212:215], v177 offset:17408
	ds_read_b128 v[216:219], v177 offset:18432
	ds_read_b128 v[220:223], v177 offset:19456
	ds_read_b128 v[224:227], v177 offset:20480
	ds_read_b128 v[228:231], v177 offset:21504
	ds_read_b128 v[232:235], v177 offset:22528
	ds_read_b128 v[236:239], v177 offset:23552
	global_load_lds_dwordx4 v[194:195], off
	s_add_i32 m0, s76, 0x2000
	s_add_u32 s76, s88, 0x40000
	v_lshl_add_u64 v[240:241], s[88:89], 0, v[148:149]
	s_addc_u32 s77, s89, 0
	s_add_i32 s80, s81, s13
	global_load_lds_dwordx4 v[240:241], off
	v_lshl_add_u64 v[242:243], s[76:77], 0, v[144:145]
	s_mov_b32 m0, s80
	v_lshl_add_u64 v[244:245], s[90:91], 0, v[146:147]
	global_load_lds_dwordx4 v[242:243], off
	v_lshl_add_u64 v[242:243], s[76:77], 0, v[148:149]
	s_add_i32 m0, s80, 0x2000
	s_nop 0
	global_load_lds_dwordx4 v[242:243], off
	v_lshl_add_u64 v[242:243], s[90:91], 0, v[142:143]
	s_mov_b32 m0, s15
	s_nop 0
	global_load_lds_dwordx4 v[242:243], off
	s_mov_b32 m0, s16
	s_nop 0
	global_load_lds_dwordx4 v[244:245], off
	s_waitcnt vmcnt(8)
	s_waitcnt lgkmcnt(0)
	s_barrier
; #define PG8_STAGE(bufoff, gbase, voff) do { _Pragma("unroll") for (int _i = 0; _i < 2; ++_i) \
;         __builtin_amdgcn_global_load_lds((const unsigned*)((const char*)(gbase) + (voff)[_i]), (PG8_LAS unsigned*)(lds + (bufoff) + ldsw + _i * 8192), 16, 0, 0); } while (0)
; #define PG8_LDA(dst, b, h) do { _Pragma("unroll") for (int m = 0; m < 4; ++m) _Pragma("unroll") for (int k = 0; k < 2; ++k) dst[m][k] = *(const PG8_LAS bf16x8*)(lds + PG8_SA(b, h) + aoff + m * 2048 + k * 1024); } while (0)
; #define PG8_LDB(dst, b, h) do { _Pragma("unroll") for (int n = 0; n < 2; ++n) _Pragma("unroll") for (int k = 0; k < 2; ++k) dst[n][k] = *(const PG8_LAS bf16x8*)(lds + PG8_SB(b, h) + boff + n * 2048 + k * 1024); } while (0)
; #define PG8_MMA(ai, bj, At, Bt) do { __builtin_amdgcn_s_setprio(1); _Pragma("unroll") for (int m = 0; m < 4; ++m) _Pragma("unroll") for (int n = 0; n < 2; ++n) _Pragma("unroll") for (int k = 0; k < 2; ++k) \
;         acc[ai][bj][m][n] = __builtin_amdgcn_mfma_f32_16x16x32_bf16(Bt[n][k], At[m][k], acc[ai][bj][m][n], 0, 0, 0); __builtin_amdgcn_s_setprio(0); } while (0)
; #define PG8_WAIT_V(n) asm volatile("s_waitcnt vmcnt(" #n ")" ::: "memory")
; #define PG8_WAIT_L(n) asm volatile("s_waitcnt lgkmcnt(" #n ")" ::: "memory")
; #define PG8_BAR __builtin_amdgcn_s_barrier()
; #define PG8_SCHED __builtin_amdgcn_sched_barrier(0)
; template <class Epi, class Sched, bool ALIGN_EPI = false, bool SP2 = false>
; __device__ __forceinline__ void gemm_phase(PG8_LAS unsigned char* lds, const Gemm g, const Sched& S, const Epi& E) {
;     ...
;             PG8_WAIT_V(8); PG8_WAIT_L(0); PG8_BAR; PG8_MMA(1, 0, At, B0); PG8_MMA(1, 1, At, B1); PG8_BAR; PG8_SCHED;
;             PG8_LDB(B0, 1, 0); PG8_LDB(B1, 1, 1); PG8_SCHED; PG8_LDA(At, 1, 0); PG8_STAGE(PG8_SA(0, 1), a2 + hstep, voffA);
;             PG8_WAIT_V(8); PG8_WAIT_L(0); PG8_BAR; PG8_MMA(0, 0, At, B0); PG8_MMA(0, 1, At, B1); PG8_BAR; PG8_SCHED;
	s_setprio 1
	s_waitcnt lgkmcnt(0)
	v_mfma_f32_16x16x32_bf16 v[68:71], v[48:51], v[190:193], v[68:71]
	v_mfma_f32_16x16x32_bf16 v[56:59], v[138:141], v[190:193], v[56:59]
	v_mfma_f32_16x16x32_bf16 v[36:39], v[138:141], v[216:219], v[36:39]
	v_mfma_f32_16x16x32_bf16 v[44:47], v[48:51], v[216:219], v[44:47]
	v_mfma_f32_16x16x32_bf16 v[28:31], v[48:51], v[224:227], v[28:31]
	v_mfma_f32_16x16x32_bf16 v[20:23], v[138:141], v[224:227], v[20:23]
	v_mfma_f32_16x16x32_bf16 v[4:7], v[138:141], v[232:235], v[4:7]
	v_mfma_f32_16x16x32_bf16 v[12:15], v[48:51], v[232:235], v[12:15]
	v_mfma_f32_16x16x32_bf16 v[68:71], v[60:63], v[212:215], v[68:71]
	v_mfma_f32_16x16x32_bf16 v[56:59], v[154:157], v[212:215], v[56:59]
	v_mfma_f32_16x16x32_bf16 v[36:39], v[154:157], v[220:223], v[36:39]
	v_mfma_f32_16x16x32_bf16 v[44:47], v[60:63], v[220:223], v[44:47]
	v_mfma_f32_16x16x32_bf16 v[28:31], v[60:63], v[228:231], v[28:31]
	v_mfma_f32_16x16x32_bf16 v[20:23], v[154:157], v[228:231], v[20:23]
	v_mfma_f32_16x16x32_bf16 v[4:7], v[154:157], v[236:239], v[4:7]
	v_mfma_f32_16x16x32_bf16 v[12:15], v[60:63], v[236:239], v[12:15]
	s_setprio 0
	s_setprio 1
	v_mfma_f32_16x16x32_bf16 v[52:55], v[182:185], v[190:193], v[52:55]
	v_mfma_f32_16x16x32_bf16 v[40:43], v[158:161], v[216:219], v[40:43]
	v_mfma_f32_16x16x32_bf16 v[32:35], v[182:185], v[216:219], v[32:35]
	v_mfma_f32_16x16x32_bf16 v[24:27], v[158:161], v[224:227], v[24:27]
	v_mfma_f32_16x16x32_bf16 v[16:19], v[182:185], v[224:227], v[16:19]
	v_mfma_f32_16x16x32_bf16 v[8:11], v[158:161], v[232:235], v[8:11]
	v_mfma_f32_16x16x32_bf16 v[0:3], v[182:185], v[232:235], v[0:3]
	v_mfma_f32_16x16x32_bf16 v[48:51], v[158:161], v[190:193], v[64:67]
	v_mfma_f32_16x16x32_bf16 v[52:55], v[186:189], v[212:215], v[52:55]
	v_mfma_f32_16x16x32_bf16 v[40:43], v[178:181], v[220:223], v[40:43]
	v_mfma_f32_16x16x32_bf16 v[32:35], v[186:189], v[220:223], v[32:35]
	v_mfma_f32_16x16x32_bf16 v[24:27], v[178:181], v[228:231], v[24:27]
	v_mfma_f32_16x16x32_bf16 v[16:19], v[186:189], v[228:231], v[16:19]
	v_mfma_f32_16x16x32_bf16 v[8:11], v[178:181], v[236:239], v[8:11]
	v_mfma_f32_16x16x32_bf16 v[0:3], v[186:189], v[236:239], v[0:3]
	v_mfma_f32_16x16x32_bf16 v[48:51], v[178:181], v[212:215], v[48:51]
	s_setprio 0
	s_barrier
	s_add_i32 s80, 0, 0x18000
	s_add_i32 s81, 0, 0x1c000
	v_add_u32_e32 v154, s80, v176
	v_add_u32_e32 v186, s81, v176
	ds_read_b128 v[60:63], v154
	ds_read_b128 v[64:67], v154 offset:1024
	ds_read_b128 v[138:141], v154 offset:2048
	ds_read_b128 v[154:157], v154 offset:3072
	ds_read_b128 v[158:161], v186
	ds_read_b128 v[178:181], v186 offset:1024
	ds_read_b128 v[182:185], v186 offset:2048
	ds_read_b128 v[186:189], v186 offset:3072
	s_add_u32 s76, s90, 0x40000
	s_addc_u32 s77, s91, 0
	s_mov_b32 m0, s17
	v_lshl_add_u64 v[246:247], s[76:77], 0, v[142:143]
	ds_read_b128 v[190:193], v177 offset:32768
	ds_read_b128 v[212:215], v177 offset:33792
	ds_read_b128 v[216:219], v177 offset:34816
	ds_read_b128 v[220:223], v177 offset:35840
	ds_read_b128 v[224:227], v177 offset:36864
	ds_read_b128 v[228:231], v177 offset:37888
	ds_read_b128 v[232:235], v177 offset:38912
	ds_read_b128 v[236:239], v177 offset:39936
	global_load_lds_dwordx4 v[246:247], off
	v_lshl_add_u64 v[246:247], s[76:77], 0, v[146:147]
	s_mov_b32 m0, s18
	s_nop 0
	global_load_lds_dwordx4 v[246:247], off
	s_waitcnt vmcnt(8)
	s_waitcnt lgkmcnt(0)
	s_barrier
	s_setprio 1
	s_waitcnt lgkmcnt(0)
	v_mfma_f32_16x16x32_bf16 v[134:137], v[60:63], v[190:193], v[134:137]
	v_mfma_f32_16x16x32_bf16 v[126:129], v[138:141], v[190:193], v[126:129]
	v_mfma_f32_16x16x32_bf16 v[110:113], v[138:141], v[216:219], v[110:113]
	v_mfma_f32_16x16x32_bf16 v[118:121], v[60:63], v[216:219], v[118:121]
	v_mfma_f32_16x16x32_bf16 v[102:105], v[60:63], v[224:227], v[102:105]
	v_mfma_f32_16x16x32_bf16 v[94:97], v[138:141], v[224:227], v[94:97]
	v_mfma_f32_16x16x32_bf16 v[76:79], v[138:141], v[232:235], v[76:79]
	v_mfma_f32_16x16x32_bf16 v[86:89], v[60:63], v[232:235], v[86:89]
	v_mfma_f32_16x16x32_bf16 v[134:137], v[64:67], v[212:215], v[134:137]
	v_mfma_f32_16x16x32_bf16 v[126:129], v[154:157], v[212:215], v[126:129]
	v_mfma_f32_16x16x32_bf16 v[110:113], v[154:157], v[220:223], v[110:113]
	v_mfma_f32_16x16x32_bf16 v[118:121], v[64:67], v[220:223], v[118:121]
	v_mfma_f32_16x16x32_bf16 v[102:105], v[64:67], v[228:231], v[102:105]
	v_mfma_f32_16x16x32_bf16 v[94:97], v[154:157], v[228:231], v[94:97]
	v_mfma_f32_16x16x32_bf16 v[76:79], v[154:157], v[236:239], v[76:79]
	v_mfma_f32_16x16x32_bf16 v[86:89], v[64:67], v[236:239], v[86:89]
	s_setprio 0
	s_setprio 1
	v_mfma_f32_16x16x32_bf16 v[130:133], v[158:161], v[190:193], v[130:133]
	v_mfma_f32_16x16x32_bf16 v[122:125], v[182:185], v[190:193], v[122:125]
	v_mfma_f32_16x16x32_bf16 v[106:109], v[182:185], v[216:219], v[106:109]
	v_mfma_f32_16x16x32_bf16 v[114:117], v[158:161], v[216:219], v[114:117]
	v_mfma_f32_16x16x32_bf16 v[98:101], v[158:161], v[224:227], v[98:101]
	v_mfma_f32_16x16x32_bf16 v[90:93], v[182:185], v[224:227], v[90:93]
	v_mfma_f32_16x16x32_bf16 v[72:75], v[182:185], v[232:235], v[72:75]
	v_mfma_f32_16x16x32_bf16 v[82:85], v[158:161], v[232:235], v[82:85]
	v_mfma_f32_16x16x32_bf16 v[130:133], v[178:181], v[212:215], v[130:133]
	v_mfma_f32_16x16x32_bf16 v[122:125], v[186:189], v[212:215], v[122:125]
	v_mfma_f32_16x16x32_bf16 v[106:109], v[186:189], v[220:223], v[106:109]
	v_mfma_f32_16x16x32_bf16 v[114:117], v[178:181], v[220:223], v[114:117]
	v_mfma_f32_16x16x32_bf16 v[98:101], v[178:181], v[228:231], v[98:101]
	v_mfma_f32_16x16x32_bf16 v[90:93], v[186:189], v[228:231], v[90:93]
	v_mfma_f32_16x16x32_bf16 v[72:75], v[186:189], v[236:239], v[72:75]
	v_mfma_f32_16x16x32_bf16 v[82:85], v[178:181], v[236:239], v[82:85]
	s_setprio 0
	s_barrier
; #define PG8_STAGE(bufoff, gbase, voff) do { _Pragma("unroll") for (int _i = 0; _i < 2; ++_i) \
;         __builtin_amdgcn_global_load_lds((const unsigned*)((const char*)(gbase) + (voff)[_i]), (PG8_LAS unsigned*)(lds + (bufoff) + ldsw + _i * 8192), 16, 0, 0); } while (0)
; #define PG8_LDA(dst, b, h) do { _Pragma("unroll") for (int m = 0; m < 4; ++m) _Pragma("unroll") for (int k = 0; k < 2; ++k) dst[m][k] = *(const PG8_LAS bf16x8*)(lds + PG8_SA(b, h) + aoff + m * 2048 + k * 1024); } while (0)
; #define PG8_MMA(ai, bj, At, Bt) do { __builtin_amdgcn_s_setprio(1); _Pragma("unroll") for (int m = 0; m < 4; ++m) _Pragma("unroll") for (int n = 0; n < 2; ++n) _Pragma("unroll") for (int k = 0; k < 2; ++k) \
;         acc[ai][bj][m][n] = __builtin_amdgcn_mfma_f32_16x16x32_bf16(Bt[n][k], At[m][k], acc[ai][bj][m][n], 0, 0, 0); __builtin_amdgcn_s_setprio(0); } while (0)
; #define PG8_WAIT_V(n) asm volatile("s_waitcnt vmcnt(" #n ")" ::: "memory")
; #define PG8_WAIT_L(n) asm volatile("s_waitcnt lgkmcnt(" #n ")" ::: "memory")
; #define PG8_BAR __builtin_amdgcn_s_barrier()
; #define PG8_SCHED __builtin_amdgcn_sched_barrier(0)
; template <class Epi, class Sched, bool ALIGN_EPI = false, bool SP2 = false>
; __device__ __forceinline__ void gemm_phase(PG8_LAS unsigned char* lds, const Gemm g, const Sched& S, const Epi& E) {
;     ...
;             PG8_LDA(At, 1, 1); PG8_STAGE(PG8_SB(1, 0), b3, voffB); PG8_STAGE(PG8_SB(1, 1), b3 + hstep, voffB); PG8_STAGE(PG8_SA(1, 0), a3, voffA);
;             PG8_WAIT_V(8); PG8_WAIT_L(0); PG8_BAR; PG8_MMA(1, 0, At, B0); PG8_MMA(1, 1, At, B1); PG8_BAR; PG8_SCHED;
	s_add_i32 s76, s80, s13
	v_lshl_add_u64 v[194:195], v[194:195], 0, s[0:1]
	s_mov_b32 m0, s76
	ds_read_b128 v[190:193], v177 offset:49152
	ds_read_b128 v[212:215], v177 offset:50176
	ds_read_b128 v[216:219], v177 offset:51200
	ds_read_b128 v[220:223], v177 offset:52224
	ds_read_b128 v[224:227], v177 offset:53248
	ds_read_b128 v[228:231], v177 offset:54272
	ds_read_b128 v[232:235], v177 offset:55296
	ds_read_b128 v[236:239], v177 offset:56320
	global_load_lds_dwordx4 v[194:195], off
	s_add_i32 m0, s76, 0x2000
	s_add_u32 s76, s88, 0x40080
	v_lshl_add_u64 v[194:195], v[240:241], 0, s[0:1]
	s_addc_u32 s77, s89, 0
	s_add_i32 s80, s81, s13
	global_load_lds_dwordx4 v[194:195], off
	v_lshl_add_u64 v[194:195], s[76:77], 0, v[144:145]
	s_mov_b32 m0, s80
	s_nop 0
	global_load_lds_dwordx4 v[194:195], off
	v_lshl_add_u64 v[194:195], s[76:77], 0, v[148:149]
	s_add_i32 m0, s80, 0x2000
	s_nop 0
	global_load_lds_dwordx4 v[194:195], off
	v_lshl_add_u64 v[194:195], v[242:243], 0, s[0:1]
	s_mov_b32 m0, s21
	s_nop 0
	global_load_lds_dwordx4 v[194:195], off
	v_lshl_add_u64 v[194:195], v[244:245], 0, s[0:1]
	s_mov_b32 m0, s33
	s_nop 0
	global_load_lds_dwordx4 v[194:195], off
	s_waitcnt vmcnt(8)
	s_waitcnt lgkmcnt(0)
	s_barrier
	s_setprio 1
	s_waitcnt lgkmcnt(0)
	v_mfma_f32_16x16x32_bf16 v[68:71], v[60:63], v[190:193], v[68:71]
	v_mfma_f32_16x16x32_bf16 v[56:59], v[138:141], v[190:193], v[56:59]
	v_mfma_f32_16x16x32_bf16 v[36:39], v[138:141], v[216:219], v[36:39]
	v_mfma_f32_16x16x32_bf16 v[44:47], v[60:63], v[216:219], v[44:47]
	v_mfma_f32_16x16x32_bf16 v[28:31], v[60:63], v[224:227], v[28:31]
	v_mfma_f32_16x16x32_bf16 v[20:23], v[138:141], v[224:227], v[20:23]
	v_mfma_f32_16x16x32_bf16 v[4:7], v[138:141], v[232:235], v[4:7]
	v_mfma_f32_16x16x32_bf16 v[12:15], v[60:63], v[232:235], v[12:15]
	v_mfma_f32_16x16x32_bf16 v[68:71], v[64:67], v[212:215], v[68:71]
	v_mfma_f32_16x16x32_bf16 v[56:59], v[154:157], v[212:215], v[56:59]
	v_mfma_f32_16x16x32_bf16 v[36:39], v[154:157], v[220:223], v[36:39]
	v_mfma_f32_16x16x32_bf16 v[44:47], v[64:67], v[220:223], v[44:47]
	v_mfma_f32_16x16x32_bf16 v[28:31], v[64:67], v[228:231], v[28:31]
	v_mfma_f32_16x16x32_bf16 v[20:23], v[154:157], v[228:231], v[20:23]
	v_mfma_f32_16x16x32_bf16 v[4:7], v[154:157], v[236:239], v[4:7]
	v_mfma_f32_16x16x32_bf16 v[12:15], v[64:67], v[236:239], v[12:15]
	s_setprio 0
	s_setprio 1
	v_mfma_f32_16x16x32_bf16 v[48:51], v[158:161], v[190:193], v[48:51]
	v_mfma_f32_16x16x32_bf16 v[64:67], v[178:181], v[212:215], v[48:51]
	v_mfma_f32_16x16x32_bf16 v[48:51], v[182:185], v[190:193], v[52:55]
	v_mfma_f32_16x16x32_bf16 v[40:43], v[158:161], v[216:219], v[40:43]
	v_mfma_f32_16x16x32_bf16 v[32:35], v[182:185], v[216:219], v[32:35]
	v_mfma_f32_16x16x32_bf16 v[24:27], v[158:161], v[224:227], v[24:27]
	v_mfma_f32_16x16x32_bf16 v[16:19], v[182:185], v[224:227], v[16:19]
	v_mfma_f32_16x16x32_bf16 v[8:11], v[158:161], v[232:235], v[8:11]
	v_mfma_f32_16x16x32_bf16 v[0:3], v[182:185], v[232:235], v[0:3]
	v_mfma_f32_16x16x32_bf16 v[52:55], v[186:189], v[212:215], v[48:51]
	v_mfma_f32_16x16x32_bf16 v[40:43], v[178:181], v[220:223], v[40:43]
	v_mfma_f32_16x16x32_bf16 v[32:35], v[186:189], v[220:223], v[32:35]
	v_mfma_f32_16x16x32_bf16 v[24:27], v[178:181], v[228:231], v[24:27]
	v_mfma_f32_16x16x32_bf16 v[16:19], v[186:189], v[228:231], v[16:19]
	v_mfma_f32_16x16x32_bf16 v[0:3], v[186:189], v[236:239], v[0:3]
	v_mfma_f32_16x16x32_bf16 v[8:11], v[178:181], v[236:239], v[8:11]
	s_setprio 0
	s_barrier
	s_add_i32 s75, s75, 2
	s_add_u32 s86, s86, 0x100
	s_addc_u32 s87, s87, 0
	s_add_u32 s69, s69, 0x100
	s_addc_u32 s71, s71, 0
	s_cmp_gt_u32 s75, 13
	s_cbranch_scc0 .LBB0_236
	s_and_b64 vcc, exec, s[30:31]
	s_cbranch_vccz .LBB0_239
	s_barrier

; #define PG8_STAGE(bufoff, gbase, voff) do { _Pragma("unroll") for (int _i = 0; _i < 2; ++_i) \
;         __builtin_amdgcn_global_load_lds((const unsigned*)((const char*)(gbase) + (voff)[_i]), (PG8_LAS unsigned*)(lds + (bufoff) + ldsw + _i * 8192), 16, 0, 0); } while (0)
; #define PG8_LDA(dst, b, h) do { _Pragma("unroll") for (int m = 0; m < 4; ++m) _Pragma("unroll") for (int k = 0; k < 2; ++k) dst[m][k] = *(const PG8_LAS bf16x8*)(lds + PG8_SA(b, h) + aoff + m * 2048 + k * 1024); } while (0)
; #define PG8_LDB(dst, b, h) do { _Pragma("unroll") for (int n = 0; n < 2; ++n) _Pragma("unroll") for (int k = 0; k < 2; ++k) dst[n][k] = *(const PG8_LAS bf16x8*)(lds + PG8_SB(b, h) + boff + n * 2048 + k * 1024); } while (0)
; #define PG8_MMA(ai, bj, At, Bt) do { __builtin_amdgcn_s_setprio(1); _Pragma("unroll") for (int m = 0; m < 4; ++m) _Pragma("unroll") for (int n = 0; n < 2; ++n) _Pragma("unroll") for (int k = 0; k < 2; ++k) \
;         acc[ai][bj][m][n] = __builtin_amdgcn_mfma_f32_16x16x32_bf16(Bt[n][k], At[m][k], acc[ai][bj][m][n], 0, 0, 0); __builtin_amdgcn_s_setprio(0); } while (0)
; #define PG8_WAIT_V(n) asm volatile("s_waitcnt vmcnt(" #n ")" ::: "memory")
; #define PG8_WAIT_L(n) asm volatile("s_waitcnt lgkmcnt(" #n ")" ::: "memory")
; #define PG8_BAR __builtin_amdgcn_s_barrier()
; #define PG8_SCHED __builtin_amdgcn_sched_barrier(0)
; template <class Epi, class Sched, bool ALIGN_EPI = false, bool SP2 = false>
; __device__ __forceinline__ void gemm_phase(PG8_LAS unsigned char* lds, const Gemm g, const Sched& S, const Epi& E) {
;     ...
;             const bool last = (t == nt - 2);
;             const char* a1 = cA + (size_t)(t + 1) * kstep;
;             const char* a2 = last ? nA : cA + (size_t)(t + 2) * kstep; const char* b2 = last ? nB : cB + (size_t)(t + 2) * kstep;
;             const char* a3 = a2 + kstep; const char* b3 = b2 + kstep;
;             if (last && has_next) S.a_ready(nxt);
;             if constexpr (SP2) {
;             PG8_LDB(B0, 0, 0); PG8_LDB(B1, 0, 1); PG8_SCHED; PG8_LDA(At, 0, 0); PG8_STAGE(PG8_SA(1, 1), a1 + hstep, voffA);
;             PG8_WAIT_V(8); PG8_WAIT_L(0); PG8_BAR; PG8_MMA(0, 0, At, B0); PG8_MMA(0, 1, At, B1); PG8_BAR; PG8_SCHED;
;             PG8_LDA(At, 0, 1); PG8_STAGE(PG8_SB(0, 0), b2, voffB); PG8_STAGE(PG8_SB(0, 1), b2 + hstep, voffB); PG8_STAGE(PG8_SA(0, 0), a2, voffA);
.LBB0_316:
	s_add_u32 s14, s40, 0xfffc0080
	s_addc_u32 s15, s41, -1
	s_add_i32 s16, 0, 0x10000
	s_cmp_eq_u32 s13, 12
	s_cselect_b32 s71, s3, s15
	s_cselect_b32 s70, s8, s14
	s_cselect_b32 s43, s9, s12
	s_cselect_b32 s42, s10, s11
	s_add_i32 s17, 0, 0x14000
	s_waitcnt lgkmcnt(0)
	v_add_u32_e32 v44, s16, v214
	v_add_u32_e32 v102, s17, v214
	ds_read_b128 v[32:35], v44
	ds_read_b128 v[36:39], v44 offset:1024
	ds_read_b128 v[40:43], v44 offset:2048
	ds_read_b128 v[44:47], v44 offset:3072
	ds_read_b128 v[90:93], v102
	ds_read_b128 v[94:97], v102 offset:1024
	ds_read_b128 v[98:101], v102 offset:2048
	ds_read_b128 v[102:105], v102 offset:3072
	v_lshl_add_u64 v[194:195], s[40:41], 0, v[178:179]
	s_add_i32 m0, s97, 0xc000
	ds_read_b128 v[182:185], v215
	ds_read_b128 v[186:189], v215 offset:1024
	ds_read_b128 v[190:193], v215 offset:2048
	ds_read_b128 v[216:219], v215 offset:3072
	ds_read_b128 v[220:223], v215 offset:4096
	ds_read_b128 v[224:227], v215 offset:5120
	ds_read_b128 v[228:231], v215 offset:6144
	ds_read_b128 v[232:235], v215 offset:7168
	global_load_lds_dwordx4 v[194:195], off
	v_lshl_add_u64 v[194:195], s[40:41], 0, v[180:181]
	s_add_i32 m0, s97, 0xe000
	s_nop 0
	global_load_lds_dwordx4 v[194:195], off
	s_waitcnt vmcnt(8)
	s_waitcnt lgkmcnt(0)
	s_barrier
	s_setprio 1
	s_waitcnt lgkmcnt(0)
	v_mfma_f32_16x16x32_bf16 v[158:161], v[32:35], v[182:185], v[158:161]
	v_mfma_f32_16x16x32_bf16 v[154:157], v[40:43], v[182:185], v[154:157]
	v_mfma_f32_16x16x32_bf16 v[138:141], v[40:43], v[190:193], v[138:141]
	v_mfma_f32_16x16x32_bf16 v[142:145], v[32:35], v[190:193], v[142:145]
	v_mfma_f32_16x16x32_bf16 v[126:129], v[32:35], v[220:223], v[126:129]
	v_mfma_f32_16x16x32_bf16 v[122:125], v[40:43], v[220:223], v[122:125]
	v_mfma_f32_16x16x32_bf16 v[106:109], v[40:43], v[228:231], v[106:109]
	v_mfma_f32_16x16x32_bf16 v[110:113], v[32:35], v[228:231], v[110:113]
	v_mfma_f32_16x16x32_bf16 v[158:161], v[36:39], v[186:189], v[158:161]
	v_mfma_f32_16x16x32_bf16 v[154:157], v[44:47], v[186:189], v[154:157]
	v_mfma_f32_16x16x32_bf16 v[138:141], v[44:47], v[216:219], v[138:141]
	v_mfma_f32_16x16x32_bf16 v[142:145], v[36:39], v[216:219], v[142:145]
	v_mfma_f32_16x16x32_bf16 v[126:129], v[36:39], v[224:227], v[126:129]
	v_mfma_f32_16x16x32_bf16 v[122:125], v[44:47], v[224:227], v[122:125]
	v_mfma_f32_16x16x32_bf16 v[106:109], v[44:47], v[232:235], v[106:109]
	v_mfma_f32_16x16x32_bf16 v[110:113], v[36:39], v[232:235], v[110:113]
	s_setprio 0
	s_setprio 1
	v_mfma_f32_16x16x32_bf16 v[150:153], v[90:93], v[182:185], v[150:153]
	v_mfma_f32_16x16x32_bf16 v[146:149], v[98:101], v[182:185], v[146:149]
	v_mfma_f32_16x16x32_bf16 v[130:133], v[98:101], v[190:193], v[130:133]
	v_mfma_f32_16x16x32_bf16 v[134:137], v[90:93], v[190:193], v[134:137]
	v_mfma_f32_16x16x32_bf16 v[118:121], v[90:93], v[220:223], v[118:121]
	v_mfma_f32_16x16x32_bf16 v[114:117], v[98:101], v[220:223], v[114:117]
	v_mfma_f32_16x16x32_bf16 v[82:85], v[98:101], v[228:231], v[82:85]
	v_mfma_f32_16x16x32_bf16 v[86:89], v[90:93], v[228:231], v[86:89]
	v_mfma_f32_16x16x32_bf16 v[150:153], v[94:97], v[186:189], v[150:153]
	v_mfma_f32_16x16x32_bf16 v[146:149], v[102:105], v[186:189], v[146:149]
	v_mfma_f32_16x16x32_bf16 v[130:133], v[102:105], v[216:219], v[130:133]
	v_mfma_f32_16x16x32_bf16 v[134:137], v[94:97], v[216:219], v[134:137]
	v_mfma_f32_16x16x32_bf16 v[118:121], v[94:97], v[224:227], v[118:121]
	v_mfma_f32_16x16x32_bf16 v[114:117], v[102:105], v[224:227], v[114:117]
	v_mfma_f32_16x16x32_bf16 v[82:85], v[102:105], v[232:235], v[82:85]
	v_mfma_f32_16x16x32_bf16 v[86:89], v[94:97], v[232:235], v[86:89]
	s_setprio 0
	s_barrier
	s_add_i32 s14, s16, s95
	v_lshl_add_u64 v[194:195], s[42:43], 0, v[174:175]
	s_mov_b32 m0, s14
	ds_read_b128 v[182:185], v215 offset:16384
	ds_read_b128 v[186:189], v215 offset:17408
	ds_read_b128 v[190:193], v215 offset:18432
	ds_read_b128 v[216:219], v215 offset:19456
	ds_read_b128 v[220:223], v215 offset:20480
	ds_read_b128 v[224:227], v215 offset:21504
	ds_read_b128 v[228:231], v215 offset:22528
	ds_read_b128 v[232:235], v215 offset:23552
	global_load_lds_dwordx4 v[194:195], off
	s_add_i32 m0, s14, 0x2000
	s_add_u32 s14, s42, 0x40000
	v_lshl_add_u64 v[236:237], s[42:43], 0, v[176:177]
	s_addc_u32 s15, s43, 0
	s_add_i32 s16, s17, s95
	global_load_lds_dwordx4 v[236:237], off
	v_lshl_add_u64 v[238:239], s[14:15], 0, v[174:175]
	s_mov_b32 m0, s16
	v_lshl_add_u64 v[240:241], s[70:71], 0, v[176:177]
	global_load_lds_dwordx4 v[238:239], off
	v_lshl_add_u64 v[238:239], s[14:15], 0, v[176:177]
	s_add_i32 m0, s16, 0x2000
	s_nop 0
	global_load_lds_dwordx4 v[238:239], off
	v_lshl_add_u64 v[238:239], s[70:71], 0, v[174:175]
	s_mov_b32 m0, s97
	s_nop 0
	global_load_lds_dwordx4 v[238:239], off
	s_mov_b32 m0, s98
	s_nop 0
	global_load_lds_dwordx4 v[240:241], off
	s_waitcnt vmcnt(8)
	s_waitcnt lgkmcnt(0)
	s_barrier
; #define PG8_STAGE(bufoff, gbase, voff) do { _Pragma("unroll") for (int _i = 0; _i < 2; ++_i) \
;         __builtin_amdgcn_global_load_lds((const unsigned*)((const char*)(gbase) + (voff)[_i]), (PG8_LAS unsigned*)(lds + (bufoff) + ldsw + _i * 8192), 16, 0, 0); } while (0)
; #define PG8_LDA(dst, b, h) do { _Pragma("unroll") for (int m = 0; m < 4; ++m) _Pragma("unroll") for (int k = 0; k < 2; ++k) dst[m][k] = *(const PG8_LAS bf16x8*)(lds + PG8_SA(b, h) + aoff + m * 2048 + k * 1024); } while (0)
; #define PG8_LDB(dst, b, h) do { _Pragma("unroll") for (int n = 0; n < 2; ++n) _Pragma("unroll") for (int k = 0; k < 2; ++k) dst[n][k] = *(const PG8_LAS bf16x8*)(lds + PG8_SB(b, h) + boff + n * 2048 + k * 1024); } while (0)
; #define PG8_MMA(ai, bj, At, Bt) do { __builtin_amdgcn_s_setprio(1); _Pragma("unroll") for (int m = 0; m < 4; ++m) _Pragma("unroll") for (int n = 0; n < 2; ++n) _Pragma("unroll") for (int k = 0; k < 2; ++k) \
;         acc[ai][bj][m][n] = __builtin_amdgcn_mfma_f32_16x16x32_bf16(Bt[n][k], At[m][k], acc[ai][bj][m][n], 0, 0, 0); __builtin_amdgcn_s_setprio(0); } while (0)
; #define PG8_WAIT_V(n) asm volatile("s_waitcnt vmcnt(" #n ")" ::: "memory")
; #define PG8_WAIT_L(n) asm volatile("s_waitcnt lgkmcnt(" #n ")" ::: "memory")
; #define PG8_BAR __builtin_amdgcn_s_barrier()
; #define PG8_SCHED __builtin_amdgcn_sched_barrier(0)
; template <class Epi, class Sched, bool ALIGN_EPI = false, bool SP2 = false>
; __device__ __forceinline__ void gemm_phase(PG8_LAS unsigned char* lds, const Gemm g, const Sched& S, const Epi& E) {
;     ...
;             PG8_WAIT_V(8); PG8_WAIT_L(0); PG8_BAR; PG8_MMA(1, 0, At, B0); PG8_MMA(1, 1, At, B1); PG8_BAR; PG8_SCHED;
;             PG8_LDB(B0, 1, 0); PG8_LDB(B1, 1, 1); PG8_SCHED; PG8_LDA(At, 1, 0); PG8_STAGE(PG8_SA(0, 1), a2 + hstep, voffA);
;             PG8_WAIT_V(8); PG8_WAIT_L(0); PG8_BAR; PG8_MMA(0, 0, At, B0); PG8_MMA(0, 1, At, B1); PG8_BAR; PG8_SCHED;
	s_setprio 1
	s_waitcnt lgkmcnt(0)
	v_mfma_f32_16x16x32_bf16 v[76:79], v[32:35], v[182:185], v[76:79]
	v_mfma_f32_16x16x32_bf16 v[72:75], v[40:43], v[182:185], v[72:75]
	v_mfma_f32_16x16x32_bf16 v[56:59], v[40:43], v[190:193], v[56:59]
	v_mfma_f32_16x16x32_bf16 v[60:63], v[32:35], v[190:193], v[60:63]
	v_mfma_f32_16x16x32_bf16 v[28:31], v[32:35], v[220:223], v[28:31]
	v_mfma_f32_16x16x32_bf16 v[24:27], v[40:43], v[220:223], v[24:27]
	v_mfma_f32_16x16x32_bf16 v[8:11], v[40:43], v[228:231], v[8:11]
	v_mfma_f32_16x16x32_bf16 v[12:15], v[32:35], v[228:231], v[12:15]
	v_mfma_f32_16x16x32_bf16 v[76:79], v[36:39], v[186:189], v[76:79]
	v_mfma_f32_16x16x32_bf16 v[72:75], v[44:47], v[186:189], v[72:75]
	v_mfma_f32_16x16x32_bf16 v[56:59], v[44:47], v[216:219], v[56:59]
	v_mfma_f32_16x16x32_bf16 v[60:63], v[36:39], v[216:219], v[60:63]
	v_mfma_f32_16x16x32_bf16 v[28:31], v[36:39], v[224:227], v[28:31]
	v_mfma_f32_16x16x32_bf16 v[24:27], v[44:47], v[224:227], v[24:27]
	v_mfma_f32_16x16x32_bf16 v[8:11], v[44:47], v[232:235], v[8:11]
	v_mfma_f32_16x16x32_bf16 v[12:15], v[36:39], v[232:235], v[12:15]
	s_setprio 0
	s_setprio 1
	v_mfma_f32_16x16x32_bf16 v[20:23], v[90:93], v[220:223], v[20:23]
	v_mfma_f32_16x16x32_bf16 v[16:19], v[98:101], v[220:223], v[16:19]
	v_mfma_f32_16x16x32_bf16 v[0:3], v[98:101], v[228:231], v[0:3]
	v_mfma_f32_16x16x32_bf16 v[4:7], v[90:93], v[228:231], v[4:7]
	v_mfma_f32_16x16x32_bf16 v[32:35], v[90:93], v[182:185], v[68:71]
	v_mfma_f32_16x16x32_bf16 v[36:39], v[98:101], v[182:185], v[64:67]
	v_mfma_f32_16x16x32_bf16 v[44:47], v[98:101], v[190:193], v[48:51]
	v_mfma_f32_16x16x32_bf16 v[40:43], v[90:93], v[190:193], v[52:55]
	v_mfma_f32_16x16x32_bf16 v[20:23], v[94:97], v[224:227], v[20:23]
	v_mfma_f32_16x16x32_bf16 v[16:19], v[102:105], v[224:227], v[16:19]
	v_mfma_f32_16x16x32_bf16 v[0:3], v[102:105], v[232:235], v[0:3]
	v_mfma_f32_16x16x32_bf16 v[4:7], v[94:97], v[232:235], v[4:7]
	v_mfma_f32_16x16x32_bf16 v[32:35], v[94:97], v[186:189], v[32:35]
	v_mfma_f32_16x16x32_bf16 v[36:39], v[102:105], v[186:189], v[36:39]
	v_mfma_f32_16x16x32_bf16 v[44:47], v[102:105], v[216:219], v[44:47]
	v_mfma_f32_16x16x32_bf16 v[40:43], v[94:97], v[216:219], v[40:43]
	s_setprio 0
	s_barrier
	s_add_i32 s16, 0, 0x18000
	s_add_i32 s17, 0, 0x1c000
	v_add_u32_e32 v68, s16, v214
	v_add_u32_e32 v102, s17, v214
	ds_read_b128 v[48:51], v68
	ds_read_b128 v[52:55], v68 offset:1024
	ds_read_b128 v[64:67], v68 offset:2048
	ds_read_b128 v[68:71], v68 offset:3072
	ds_read_b128 v[90:93], v102
	ds_read_b128 v[94:97], v102 offset:1024
	ds_read_b128 v[98:101], v102 offset:2048
	ds_read_b128 v[102:105], v102 offset:3072
	s_add_u32 s14, s70, 0x40000
	s_addc_u32 s15, s71, 0
	s_mov_b32 m0, s99
	v_lshl_add_u64 v[242:243], s[14:15], 0, v[174:175]
	ds_read_b128 v[182:185], v215 offset:32768
	ds_read_b128 v[186:189], v215 offset:33792
	ds_read_b128 v[190:193], v215 offset:34816
	ds_read_b128 v[216:219], v215 offset:35840
	ds_read_b128 v[220:223], v215 offset:36864
	ds_read_b128 v[224:227], v215 offset:37888
	ds_read_b128 v[228:231], v215 offset:38912
	ds_read_b128 v[232:235], v215 offset:39936
	global_load_lds_dwordx4 v[242:243], off
	v_lshl_add_u64 v[242:243], s[14:15], 0, v[176:177]
	s_mov_b32 m0, s94
	s_nop 0
	global_load_lds_dwordx4 v[242:243], off
	s_waitcnt vmcnt(8)
	s_waitcnt lgkmcnt(0)
	s_barrier
	s_setprio 1
	s_waitcnt lgkmcnt(0)
	v_mfma_f32_16x16x32_bf16 v[158:161], v[48:51], v[182:185], v[158:161]
	v_mfma_f32_16x16x32_bf16 v[154:157], v[64:67], v[182:185], v[154:157]
	v_mfma_f32_16x16x32_bf16 v[138:141], v[64:67], v[190:193], v[138:141]
	v_mfma_f32_16x16x32_bf16 v[142:145], v[48:51], v[190:193], v[142:145]
	v_mfma_f32_16x16x32_bf16 v[126:129], v[48:51], v[220:223], v[126:129]
	v_mfma_f32_16x16x32_bf16 v[122:125], v[64:67], v[220:223], v[122:125]
	v_mfma_f32_16x16x32_bf16 v[106:109], v[64:67], v[228:231], v[106:109]
	v_mfma_f32_16x16x32_bf16 v[110:113], v[48:51], v[228:231], v[110:113]
	v_mfma_f32_16x16x32_bf16 v[158:161], v[52:55], v[186:189], v[158:161]
	v_mfma_f32_16x16x32_bf16 v[154:157], v[68:71], v[186:189], v[154:157]
	v_mfma_f32_16x16x32_bf16 v[138:141], v[68:71], v[216:219], v[138:141]
	v_mfma_f32_16x16x32_bf16 v[142:145], v[52:55], v[216:219], v[142:145]
	v_mfma_f32_16x16x32_bf16 v[126:129], v[52:55], v[224:227], v[126:129]
	v_mfma_f32_16x16x32_bf16 v[122:125], v[68:71], v[224:227], v[122:125]
	v_mfma_f32_16x16x32_bf16 v[106:109], v[68:71], v[232:235], v[106:109]
	v_mfma_f32_16x16x32_bf16 v[110:113], v[52:55], v[232:235], v[110:113]
	s_setprio 0
	s_setprio 1
	v_mfma_f32_16x16x32_bf16 v[150:153], v[90:93], v[182:185], v[150:153]
	v_mfma_f32_16x16x32_bf16 v[146:149], v[98:101], v[182:185], v[146:149]
	v_mfma_f32_16x16x32_bf16 v[130:133], v[98:101], v[190:193], v[130:133]
	v_mfma_f32_16x16x32_bf16 v[134:137], v[90:93], v[190:193], v[134:137]
	v_mfma_f32_16x16x32_bf16 v[118:121], v[90:93], v[220:223], v[118:121]
	v_mfma_f32_16x16x32_bf16 v[114:117], v[98:101], v[220:223], v[114:117]
	v_mfma_f32_16x16x32_bf16 v[82:85], v[98:101], v[228:231], v[82:85]
	v_mfma_f32_16x16x32_bf16 v[86:89], v[90:93], v[228:231], v[86:89]
	v_mfma_f32_16x16x32_bf16 v[150:153], v[94:97], v[186:189], v[150:153]
	v_mfma_f32_16x16x32_bf16 v[146:149], v[102:105], v[186:189], v[146:149]
	v_mfma_f32_16x16x32_bf16 v[130:133], v[102:105], v[216:219], v[130:133]
	v_mfma_f32_16x16x32_bf16 v[134:137], v[94:97], v[216:219], v[134:137]
	v_mfma_f32_16x16x32_bf16 v[118:121], v[94:97], v[224:227], v[118:121]
	v_mfma_f32_16x16x32_bf16 v[114:117], v[102:105], v[224:227], v[114:117]
	v_mfma_f32_16x16x32_bf16 v[82:85], v[102:105], v[232:235], v[82:85]
	v_mfma_f32_16x16x32_bf16 v[86:89], v[94:97], v[232:235], v[86:89]
	s_setprio 0
	s_barrier
; #define PG8_STAGE(bufoff, gbase, voff) do { _Pragma("unroll") for (int _i = 0; _i < 2; ++_i) \
;         __builtin_amdgcn_global_load_lds((const unsigned*)((const char*)(gbase) + (voff)[_i]), (PG8_LAS unsigned*)(lds + (bufoff) + ldsw + _i * 8192), 16, 0, 0); } while (0)
; #define PG8_LDA(dst, b, h) do { _Pragma("unroll") for (int m = 0; m < 4; ++m) _Pragma("unroll") for (int k = 0; k < 2; ++k) dst[m][k] = *(const PG8_LAS bf16x8*)(lds + PG8_SA(b, h) + aoff + m * 2048 + k * 1024); } while (0)
; #define PG8_MMA(ai, bj, At, Bt) do { __builtin_amdgcn_s_setprio(1); _Pragma("unroll") for (int m = 0; m < 4; ++m) _Pragma("unroll") for (int n = 0; n < 2; ++n) _Pragma("unroll") for (int k = 0; k < 2; ++k) \
;         acc[ai][bj][m][n] = __builtin_amdgcn_mfma_f32_16x16x32_bf16(Bt[n][k], At[m][k], acc[ai][bj][m][n], 0, 0, 0); __builtin_amdgcn_s_setprio(0); } while (0)
; #define PG8_WAIT_V(n) asm volatile("s_waitcnt vmcnt(" #n ")" ::: "memory")
; #define PG8_WAIT_L(n) asm volatile("s_waitcnt lgkmcnt(" #n ")" ::: "memory")
; #define PG8_BAR __builtin_amdgcn_s_barrier()
; #define PG8_SCHED __builtin_amdgcn_sched_barrier(0)
; template <class Epi, class Sched, bool ALIGN_EPI = false, bool SP2 = false>
; __device__ __forceinline__ void gemm_phase(PG8_LAS unsigned char* lds, const Gemm g, const Sched& S, const Epi& E) {
;     ...
;             PG8_LDA(At, 1, 1); PG8_STAGE(PG8_SB(1, 0), b3, voffB); PG8_STAGE(PG8_SB(1, 1), b3 + hstep, voffB); PG8_STAGE(PG8_SA(1, 0), a3, voffA);
;             PG8_WAIT_V(8); PG8_WAIT_L(0); PG8_BAR; PG8_MMA(1, 0, At, B0); PG8_MMA(1, 1, At, B1); PG8_BAR; PG8_SCHED;
	s_add_i32 s14, s16, s95
	v_lshl_add_u64 v[194:195], v[194:195], 0, s[0:1]
	s_mov_b32 m0, s14
	ds_read_b128 v[182:185], v215 offset:49152
	ds_read_b128 v[186:189], v215 offset:50176
	ds_read_b128 v[190:193], v215 offset:51200
	ds_read_b128 v[216:219], v215 offset:52224
	ds_read_b128 v[220:223], v215 offset:53248
	ds_read_b128 v[224:227], v215 offset:54272
	ds_read_b128 v[228:231], v215 offset:55296
	ds_read_b128 v[232:235], v215 offset:56320
	global_load_lds_dwordx4 v[194:195], off
	s_add_i32 m0, s14, 0x2000
	s_add_u32 s14, s42, 0x40080
	v_lshl_add_u64 v[194:195], v[236:237], 0, s[0:1]
	s_addc_u32 s15, s43, 0
	s_add_i32 s16, s17, s95
	global_load_lds_dwordx4 v[194:195], off
	v_lshl_add_u64 v[194:195], s[14:15], 0, v[174:175]
	s_mov_b32 m0, s16
	s_nop 0
	global_load_lds_dwordx4 v[194:195], off
	v_lshl_add_u64 v[194:195], s[14:15], 0, v[176:177]
	s_add_i32 m0, s16, 0x2000
	s_nop 0
	global_load_lds_dwordx4 v[194:195], off
	v_lshl_add_u64 v[194:195], v[238:239], 0, s[0:1]
	s_mov_b32 m0, s44
	s_nop 0
	global_load_lds_dwordx4 v[194:195], off
	v_lshl_add_u64 v[194:195], v[240:241], 0, s[0:1]
	s_mov_b32 m0, s45
	s_nop 0
	global_load_lds_dwordx4 v[194:195], off
	s_waitcnt vmcnt(8)
	s_waitcnt lgkmcnt(0)
	s_barrier
	s_setprio 1
	s_waitcnt lgkmcnt(0)
	v_mfma_f32_16x16x32_bf16 v[76:79], v[48:51], v[182:185], v[76:79]
	v_mfma_f32_16x16x32_bf16 v[72:75], v[64:67], v[182:185], v[72:75]
	v_mfma_f32_16x16x32_bf16 v[56:59], v[64:67], v[190:193], v[56:59]
	v_mfma_f32_16x16x32_bf16 v[60:63], v[48:51], v[190:193], v[60:63]
	v_mfma_f32_16x16x32_bf16 v[28:31], v[48:51], v[220:223], v[28:31]
	v_mfma_f32_16x16x32_bf16 v[24:27], v[64:67], v[220:223], v[24:27]
	v_mfma_f32_16x16x32_bf16 v[8:11], v[64:67], v[228:231], v[8:11]
	v_mfma_f32_16x16x32_bf16 v[12:15], v[48:51], v[228:231], v[12:15]
	v_mfma_f32_16x16x32_bf16 v[76:79], v[52:55], v[186:189], v[76:79]
	v_mfma_f32_16x16x32_bf16 v[72:75], v[68:71], v[186:189], v[72:75]
	v_mfma_f32_16x16x32_bf16 v[56:59], v[68:71], v[216:219], v[56:59]
	v_mfma_f32_16x16x32_bf16 v[60:63], v[52:55], v[216:219], v[60:63]
	v_mfma_f32_16x16x32_bf16 v[28:31], v[52:55], v[224:227], v[28:31]
	v_mfma_f32_16x16x32_bf16 v[24:27], v[68:71], v[224:227], v[24:27]
	v_mfma_f32_16x16x32_bf16 v[8:11], v[68:71], v[232:235], v[8:11]
	v_mfma_f32_16x16x32_bf16 v[12:15], v[52:55], v[232:235], v[12:15]
	s_setprio 0
	s_setprio 1
	v_mfma_f32_16x16x32_bf16 v[32:35], v[90:93], v[182:185], v[32:35]
	v_mfma_f32_16x16x32_bf16 v[68:71], v[94:97], v[186:189], v[32:35]
	v_mfma_f32_16x16x32_bf16 v[32:35], v[98:101], v[182:185], v[36:39]
	v_mfma_f32_16x16x32_bf16 v[64:67], v[102:105], v[186:189], v[32:35]
	v_mfma_f32_16x16x32_bf16 v[32:35], v[90:93], v[190:193], v[40:43]
	v_mfma_f32_16x16x32_bf16 v[52:55], v[94:97], v[216:219], v[32:35]
	v_mfma_f32_16x16x32_bf16 v[32:35], v[98:101], v[190:193], v[44:47]
	v_mfma_f32_16x16x32_bf16 v[20:23], v[90:93], v[220:223], v[20:23]
	v_mfma_f32_16x16x32_bf16 v[16:19], v[98:101], v[220:223], v[16:19]
	v_mfma_f32_16x16x32_bf16 v[4:7], v[90:93], v[228:231], v[4:7]
	v_mfma_f32_16x16x32_bf16 v[0:3], v[98:101], v[228:231], v[0:3]
	v_mfma_f32_16x16x32_bf16 v[48:51], v[102:105], v[216:219], v[32:35]
	v_mfma_f32_16x16x32_bf16 v[20:23], v[94:97], v[224:227], v[20:23]
	v_mfma_f32_16x16x32_bf16 v[16:19], v[102:105], v[224:227], v[16:19]
	v_mfma_f32_16x16x32_bf16 v[0:3], v[102:105], v[232:235], v[0:3]
	v_mfma_f32_16x16x32_bf16 v[4:7], v[94:97], v[232:235], v[4:7]
	s_setprio 0
	s_barrier
	s_add_i32 s13, s13, 2
	s_add_u32 s40, s40, 0x100
	s_addc_u32 s41, s41, 0
	s_add_u32 s11, s11, 0x100
	s_addc_u32 s12, s12, 0
	s_cmp_gt_u32 s13, 13
	s_cbranch_scc0 .LBB0_316
	s_and_b64 vcc, exec, s[22:23]
	s_cbranch_vccz .LBB0_319
	s_barrier

; #define PG8_STAGE(bufoff, gbase, voff) do { _Pragma("unroll") for (int _i = 0; _i < 2; ++_i) \
;         __builtin_amdgcn_global_load_lds((const unsigned*)((const char*)(gbase) + (voff)[_i]), (PG8_LAS unsigned*)(lds + (bufoff) + ldsw + _i * 8192), 16, 0, 0); } while (0)
; #define PG8_LDA(dst, b, h) do { _Pragma("unroll") for (int m = 0; m < 4; ++m) _Pragma("unroll") for (int k = 0; k < 2; ++k) dst[m][k] = *(const PG8_LAS bf16x8*)(lds + PG8_SA(b, h) + aoff + m * 2048 + k * 1024); } while (0)
; #define PG8_LDB(dst, b, h) do { _Pragma("unroll") for (int n = 0; n < 2; ++n) _Pragma("unroll") for (int k = 0; k < 2; ++k) dst[n][k] = *(const PG8_LAS bf16x8*)(lds + PG8_SB(b, h) + boff + n * 2048 + k * 1024); } while (0)
; #define PG8_MMA(ai, bj, At, Bt) do { __builtin_amdgcn_s_setprio(1); _Pragma("unroll") for (int m = 0; m < 4; ++m) _Pragma("unroll") for (int n = 0; n < 2; ++n) _Pragma("unroll") for (int k = 0; k < 2; ++k) \
;         acc[ai][bj][m][n] = __builtin_amdgcn_mfma_f32_16x16x32_bf16(Bt[n][k], At[m][k], acc[ai][bj][m][n], 0, 0, 0); __builtin_amdgcn_s_setprio(0); } while (0)
; #define PG8_WAIT_V(n) asm volatile("s_waitcnt vmcnt(" #n ")" ::: "memory")
; #define PG8_WAIT_L(n) asm volatile("s_waitcnt lgkmcnt(" #n ")" ::: "memory")
; #define PG8_BAR __builtin_amdgcn_s_barrier()
; #define PG8_SCHED __builtin_amdgcn_sched_barrier(0)
; template <class Epi, class Sched, bool ALIGN_EPI = false, bool SP2 = false>
; __device__ __forceinline__ void gemm_phase(PG8_LAS unsigned char* lds, const Gemm g, const Sched& S, const Epi& E) {
;     ...
;             const bool last = (t == nt - 2);
;             const char* a1 = cA + (size_t)(t + 1) * kstep;
;             const char* a2 = last ? nA : cA + (size_t)(t + 2) * kstep; const char* b2 = last ? nB : cB + (size_t)(t + 2) * kstep;
;             const char* a3 = a2 + kstep; const char* b3 = b2 + kstep;
;             if (last && has_next) S.a_ready(nxt);
;             if constexpr (SP2) {
;             PG8_LDB(B0, 0, 0); PG8_LDB(B1, 0, 1); PG8_SCHED; PG8_LDA(At, 0, 0); PG8_STAGE(PG8_SA(1, 1), a1 + hstep, voffA);
;             PG8_WAIT_V(8); PG8_WAIT_L(0); PG8_BAR; PG8_MMA(0, 0, At, B0); PG8_MMA(0, 1, At, B1); PG8_BAR; PG8_SCHED;
;             PG8_LDA(At, 0, 1); PG8_STAGE(PG8_SB(0, 0), b2, voffB); PG8_STAGE(PG8_SB(0, 1), b2 + hstep, voffB); PG8_STAGE(PG8_SA(0, 0), a2, voffA);
.LBB0_647:
	s_add_i32 s71, s42, 2
	s_add_u32 s81, s38, 0x80
	s_addc_u32 s43, s39, 0
	s_add_i32 s94, 0, 0x10000
	s_cmp_eq_u32 s24, s42
	s_cselect_b32 s43, s27, s43
	s_cselect_b32 s42, s26, s81
	s_cselect_b32 s93, s91, s45
	s_cselect_b32 s92, s90, s41
	s_add_i32 s81, 0, 0x14000
	v_add_u32_e32 v142, s94, v213
	v_add_u32_e32 v151, s81, v213
	ds_read_b128 v[130:133], v142
	ds_read_b128 v[134:137], v142 offset:1024
	ds_read_b128 v[138:141], v142 offset:2048
	ds_read_b128 v[142:145], v142 offset:3072
	ds_read_b128 v[158:161], v151
	ds_read_b128 v[174:177], v151 offset:1024
	ds_read_b128 v[178:181], v151 offset:2048
	ds_read_b128 v[182:185], v151 offset:3072
	v_lshl_add_u64 v[194:195], s[38:39], 0, v[154:155]
	s_add_i32 m0, s17, 0xc000
	ds_read_b128 v[186:189], v214
	ds_read_b128 v[190:193], v214 offset:1024
	ds_read_b128 v[216:219], v214 offset:2048
	ds_read_b128 v[220:223], v214 offset:3072
	ds_read_b128 v[224:227], v214 offset:4096
	ds_read_b128 v[228:231], v214 offset:5120
	ds_read_b128 v[232:235], v214 offset:6144
	ds_read_b128 v[236:239], v214 offset:7168
	global_load_lds_dwordx4 v[194:195], off
	v_lshl_add_u64 v[194:195], s[38:39], 0, v[156:157]
	s_add_i32 m0, s17, 0xe000
	s_nop 0
	global_load_lds_dwordx4 v[194:195], off
	s_waitcnt vmcnt(8)
	s_waitcnt lgkmcnt(0)
	s_barrier
	s_setprio 1
	s_waitcnt lgkmcnt(0)
	v_mfma_f32_16x16x32_bf16 v[126:129], v[130:133], v[186:189], v[126:129]
	v_mfma_f32_16x16x32_bf16 v[122:125], v[138:141], v[186:189], v[122:125]
	v_mfma_f32_16x16x32_bf16 v[106:109], v[138:141], v[216:219], v[106:109]
	v_mfma_f32_16x16x32_bf16 v[110:113], v[130:133], v[216:219], v[110:113]
	v_mfma_f32_16x16x32_bf16 v[94:97], v[130:133], v[224:227], v[94:97]
	v_mfma_f32_16x16x32_bf16 v[90:93], v[138:141], v[224:227], v[90:93]
	v_mfma_f32_16x16x32_bf16 v[72:75], v[138:141], v[232:235], v[72:75]
	v_mfma_f32_16x16x32_bf16 v[76:79], v[130:133], v[232:235], v[76:79]
	v_mfma_f32_16x16x32_bf16 v[126:129], v[134:137], v[190:193], v[126:129]
	v_mfma_f32_16x16x32_bf16 v[122:125], v[142:145], v[190:193], v[122:125]
	v_mfma_f32_16x16x32_bf16 v[106:109], v[142:145], v[220:223], v[106:109]
	v_mfma_f32_16x16x32_bf16 v[110:113], v[134:137], v[220:223], v[110:113]
	v_mfma_f32_16x16x32_bf16 v[94:97], v[134:137], v[228:231], v[94:97]
	v_mfma_f32_16x16x32_bf16 v[90:93], v[142:145], v[228:231], v[90:93]
	v_mfma_f32_16x16x32_bf16 v[72:75], v[142:145], v[236:239], v[72:75]
	v_mfma_f32_16x16x32_bf16 v[76:79], v[134:137], v[236:239], v[76:79]
	s_setprio 0
	s_setprio 1
	v_mfma_f32_16x16x32_bf16 v[118:121], v[158:161], v[186:189], v[118:121]
	v_mfma_f32_16x16x32_bf16 v[114:117], v[178:181], v[186:189], v[114:117]
	v_mfma_f32_16x16x32_bf16 v[98:101], v[178:181], v[216:219], v[98:101]
	v_mfma_f32_16x16x32_bf16 v[102:105], v[158:161], v[216:219], v[102:105]
	v_mfma_f32_16x16x32_bf16 v[86:89], v[158:161], v[224:227], v[86:89]
	v_mfma_f32_16x16x32_bf16 v[82:85], v[178:181], v[224:227], v[82:85]
	v_mfma_f32_16x16x32_bf16 v[64:67], v[178:181], v[232:235], v[64:67]
	v_mfma_f32_16x16x32_bf16 v[68:71], v[158:161], v[232:235], v[68:71]
	v_mfma_f32_16x16x32_bf16 v[118:121], v[174:177], v[190:193], v[118:121]
	v_mfma_f32_16x16x32_bf16 v[114:117], v[182:185], v[190:193], v[114:117]
	v_mfma_f32_16x16x32_bf16 v[98:101], v[182:185], v[220:223], v[98:101]
	v_mfma_f32_16x16x32_bf16 v[102:105], v[174:177], v[220:223], v[102:105]
	v_mfma_f32_16x16x32_bf16 v[86:89], v[174:177], v[228:231], v[86:89]
	v_mfma_f32_16x16x32_bf16 v[82:85], v[182:185], v[228:231], v[82:85]
	v_mfma_f32_16x16x32_bf16 v[64:67], v[182:185], v[236:239], v[64:67]
	v_mfma_f32_16x16x32_bf16 v[68:71], v[174:177], v[236:239], v[68:71]
	s_setprio 0
	s_barrier
	s_add_i32 s94, s94, s16
	v_lshl_add_u64 v[194:195], s[92:93], 0, v[146:147]
	s_mov_b32 m0, s94
	ds_read_b128 v[186:189], v214 offset:16384
	ds_read_b128 v[190:193], v214 offset:17408
	ds_read_b128 v[216:219], v214 offset:18432
	ds_read_b128 v[220:223], v214 offset:19456
	ds_read_b128 v[224:227], v214 offset:20480
	ds_read_b128 v[228:231], v214 offset:21504
	ds_read_b128 v[232:235], v214 offset:22528
	ds_read_b128 v[236:239], v214 offset:23552
	global_load_lds_dwordx4 v[194:195], off
	s_add_i32 m0, s94, 0x2000
	v_lshl_add_u64 v[240:241], s[92:93], 0, v[148:149]
	s_add_u32 s92, s92, s30
	s_addc_u32 s93, s93, 0
	s_add_i32 s81, s81, s16
	global_load_lds_dwordx4 v[240:241], off
	v_lshl_add_u64 v[242:243], s[92:93], 0, v[146:147]
	s_mov_b32 m0, s81
	v_lshl_add_u64 v[244:245], s[92:93], 0, v[148:149]
	global_load_lds_dwordx4 v[242:243], off
	s_add_i32 m0, s81, 0x2000
	v_lshl_add_u64 v[246:247], s[42:43], 0, v[146:147]
	global_load_lds_dwordx4 v[244:245], off
	s_mov_b32 m0, s17
	v_lshl_add_u64 v[248:249], s[42:43], 0, v[148:149]
	global_load_lds_dwordx4 v[246:247], off
	s_mov_b32 m0, s18
	s_nop 0
	global_load_lds_dwordx4 v[248:249], off
	s_waitcnt vmcnt(8)
	s_waitcnt lgkmcnt(0)
	s_barrier
; #define PG8_STAGE(bufoff, gbase, voff) do { _Pragma("unroll") for (int _i = 0; _i < 2; ++_i) \
;         __builtin_amdgcn_global_load_lds((const unsigned*)((const char*)(gbase) + (voff)[_i]), (PG8_LAS unsigned*)(lds + (bufoff) + ldsw + _i * 8192), 16, 0, 0); } while (0)
; #define PG8_LDA(dst, b, h) do { _Pragma("unroll") for (int m = 0; m < 4; ++m) _Pragma("unroll") for (int k = 0; k < 2; ++k) dst[m][k] = *(const PG8_LAS bf16x8*)(lds + PG8_SA(b, h) + aoff + m * 2048 + k * 1024); } while (0)
; #define PG8_LDB(dst, b, h) do { _Pragma("unroll") for (int n = 0; n < 2; ++n) _Pragma("unroll") for (int k = 0; k < 2; ++k) dst[n][k] = *(const PG8_LAS bf16x8*)(lds + PG8_SB(b, h) + boff + n * 2048 + k * 1024); } while (0)
; #define PG8_MMA(ai, bj, At, Bt) do { __builtin_amdgcn_s_setprio(1); _Pragma("unroll") for (int m = 0; m < 4; ++m) _Pragma("unroll") for (int n = 0; n < 2; ++n) _Pragma("unroll") for (int k = 0; k < 2; ++k) \
;         acc[ai][bj][m][n] = __builtin_amdgcn_mfma_f32_16x16x32_bf16(Bt[n][k], At[m][k], acc[ai][bj][m][n], 0, 0, 0); __builtin_amdgcn_s_setprio(0); } while (0)
; #define PG8_WAIT_V(n) asm volatile("s_waitcnt vmcnt(" #n ")" ::: "memory")
; #define PG8_WAIT_L(n) asm volatile("s_waitcnt lgkmcnt(" #n ")" ::: "memory")
; #define PG8_BAR __builtin_amdgcn_s_barrier()
; #define PG8_SCHED __builtin_amdgcn_sched_barrier(0)
; template <class Epi, class Sched, bool ALIGN_EPI = false, bool SP2 = false>
; __device__ __forceinline__ void gemm_phase(PG8_LAS unsigned char* lds, const Gemm g, const Sched& S, const Epi& E) {
;     ...
;             PG8_WAIT_V(8); PG8_WAIT_L(0); PG8_BAR; PG8_MMA(1, 0, At, B0); PG8_MMA(1, 1, At, B1); PG8_BAR; PG8_SCHED;
;             PG8_LDB(B0, 1, 0); PG8_LDB(B1, 1, 1); PG8_SCHED; PG8_LDA(At, 1, 0); PG8_STAGE(PG8_SA(0, 1), a2 + hstep, voffA);
;             PG8_WAIT_V(8); PG8_WAIT_L(0); PG8_BAR; PG8_MMA(0, 0, At, B0); PG8_MMA(0, 1, At, B1); PG8_BAR; PG8_SCHED;
	s_setprio 1
	s_waitcnt lgkmcnt(0)
	v_mfma_f32_16x16x32_bf16 v[60:63], v[130:133], v[186:189], v[60:63]
	v_mfma_f32_16x16x32_bf16 v[56:59], v[138:141], v[186:189], v[56:59]
	v_mfma_f32_16x16x32_bf16 v[40:43], v[138:141], v[216:219], v[40:43]
	v_mfma_f32_16x16x32_bf16 v[44:47], v[130:133], v[216:219], v[44:47]
	v_mfma_f32_16x16x32_bf16 v[28:31], v[130:133], v[224:227], v[28:31]
	v_mfma_f32_16x16x32_bf16 v[24:27], v[138:141], v[224:227], v[24:27]
	v_mfma_f32_16x16x32_bf16 v[8:11], v[138:141], v[232:235], v[8:11]
	v_mfma_f32_16x16x32_bf16 v[12:15], v[130:133], v[232:235], v[12:15]
	v_mfma_f32_16x16x32_bf16 v[60:63], v[134:137], v[190:193], v[60:63]
	v_mfma_f32_16x16x32_bf16 v[56:59], v[142:145], v[190:193], v[56:59]
	v_mfma_f32_16x16x32_bf16 v[40:43], v[142:145], v[220:223], v[40:43]
	v_mfma_f32_16x16x32_bf16 v[44:47], v[134:137], v[220:223], v[44:47]
	v_mfma_f32_16x16x32_bf16 v[28:31], v[134:137], v[228:231], v[28:31]
	v_mfma_f32_16x16x32_bf16 v[24:27], v[142:145], v[228:231], v[24:27]
	v_mfma_f32_16x16x32_bf16 v[8:11], v[142:145], v[236:239], v[8:11]
	v_mfma_f32_16x16x32_bf16 v[12:15], v[134:137], v[236:239], v[12:15]
	s_setprio 0
	s_setprio 1
	v_mfma_f32_16x16x32_bf16 v[52:55], v[158:161], v[186:189], v[52:55]
	v_mfma_f32_16x16x32_bf16 v[48:51], v[178:181], v[186:189], v[48:51]
	v_mfma_f32_16x16x32_bf16 v[32:35], v[178:181], v[216:219], v[32:35]
	v_mfma_f32_16x16x32_bf16 v[36:39], v[158:161], v[216:219], v[36:39]
	v_mfma_f32_16x16x32_bf16 v[20:23], v[158:161], v[224:227], v[20:23]
	v_mfma_f32_16x16x32_bf16 v[16:19], v[178:181], v[224:227], v[16:19]
	v_mfma_f32_16x16x32_bf16 v[0:3], v[178:181], v[232:235], v[0:3]
	v_mfma_f32_16x16x32_bf16 v[4:7], v[158:161], v[232:235], v[4:7]
	v_mfma_f32_16x16x32_bf16 v[52:55], v[174:177], v[190:193], v[52:55]
	v_mfma_f32_16x16x32_bf16 v[48:51], v[182:185], v[190:193], v[48:51]
	v_mfma_f32_16x16x32_bf16 v[32:35], v[182:185], v[220:223], v[32:35]
	v_mfma_f32_16x16x32_bf16 v[36:39], v[174:177], v[220:223], v[36:39]
	v_mfma_f32_16x16x32_bf16 v[20:23], v[174:177], v[228:231], v[20:23]
	v_mfma_f32_16x16x32_bf16 v[16:19], v[182:185], v[228:231], v[16:19]
	v_mfma_f32_16x16x32_bf16 v[0:3], v[182:185], v[236:239], v[0:3]
	v_mfma_f32_16x16x32_bf16 v[4:7], v[174:177], v[236:239], v[4:7]
	s_setprio 0
	s_barrier
	s_add_i32 s81, 0, 0x18000
	s_add_i32 s92, 0, 0x1c000
	v_add_u32_e32 v142, s81, v213
	v_add_u32_e32 v151, s92, v213
	ds_read_b128 v[130:133], v142
	ds_read_b128 v[134:137], v142 offset:1024
	ds_read_b128 v[138:141], v142 offset:2048
	ds_read_b128 v[142:145], v142 offset:3072
	ds_read_b128 v[158:161], v151
	ds_read_b128 v[174:177], v151 offset:1024
	ds_read_b128 v[178:181], v151 offset:2048
	ds_read_b128 v[182:185], v151 offset:3072
	s_add_u32 s42, s42, s30
	s_addc_u32 s43, s43, 0
	s_mov_b32 m0, s19
	v_lshl_add_u64 v[250:251], s[42:43], 0, v[146:147]
	ds_read_b128 v[186:189], v214 offset:32768
	ds_read_b128 v[190:193], v214 offset:33792
	ds_read_b128 v[216:219], v214 offset:34816
	ds_read_b128 v[220:223], v214 offset:35840
	ds_read_b128 v[224:227], v214 offset:36864
	ds_read_b128 v[228:231], v214 offset:37888
	ds_read_b128 v[232:235], v214 offset:38912
	ds_read_b128 v[236:239], v214 offset:39936
	global_load_lds_dwordx4 v[250:251], off
	v_lshl_add_u64 v[250:251], s[42:43], 0, v[148:149]
	s_mov_b32 m0, s20
	s_nop 0
	global_load_lds_dwordx4 v[250:251], off
	s_waitcnt vmcnt(8)
	s_waitcnt lgkmcnt(0)
	s_barrier
	s_setprio 1
	s_waitcnt lgkmcnt(0)
	v_mfma_f32_16x16x32_bf16 v[126:129], v[130:133], v[186:189], v[126:129]
	v_mfma_f32_16x16x32_bf16 v[122:125], v[138:141], v[186:189], v[122:125]
	v_mfma_f32_16x16x32_bf16 v[106:109], v[138:141], v[216:219], v[106:109]
	v_mfma_f32_16x16x32_bf16 v[110:113], v[130:133], v[216:219], v[110:113]
	v_mfma_f32_16x16x32_bf16 v[94:97], v[130:133], v[224:227], v[94:97]
	v_mfma_f32_16x16x32_bf16 v[90:93], v[138:141], v[224:227], v[90:93]
	v_mfma_f32_16x16x32_bf16 v[72:75], v[138:141], v[232:235], v[72:75]
	v_mfma_f32_16x16x32_bf16 v[76:79], v[130:133], v[232:235], v[76:79]
	v_mfma_f32_16x16x32_bf16 v[126:129], v[134:137], v[190:193], v[126:129]
	v_mfma_f32_16x16x32_bf16 v[122:125], v[142:145], v[190:193], v[122:125]
	v_mfma_f32_16x16x32_bf16 v[106:109], v[142:145], v[220:223], v[106:109]
	v_mfma_f32_16x16x32_bf16 v[110:113], v[134:137], v[220:223], v[110:113]
	v_mfma_f32_16x16x32_bf16 v[94:97], v[134:137], v[228:231], v[94:97]
	v_mfma_f32_16x16x32_bf16 v[90:93], v[142:145], v[228:231], v[90:93]
	v_mfma_f32_16x16x32_bf16 v[72:75], v[142:145], v[236:239], v[72:75]
	v_mfma_f32_16x16x32_bf16 v[76:79], v[134:137], v[236:239], v[76:79]
	s_setprio 0
	s_setprio 1
	v_mfma_f32_16x16x32_bf16 v[118:121], v[158:161], v[186:189], v[118:121]
	v_mfma_f32_16x16x32_bf16 v[114:117], v[178:181], v[186:189], v[114:117]
	v_mfma_f32_16x16x32_bf16 v[98:101], v[178:181], v[216:219], v[98:101]
	v_mfma_f32_16x16x32_bf16 v[102:105], v[158:161], v[216:219], v[102:105]
	v_mfma_f32_16x16x32_bf16 v[86:89], v[158:161], v[224:227], v[86:89]
	v_mfma_f32_16x16x32_bf16 v[82:85], v[178:181], v[224:227], v[82:85]
	v_mfma_f32_16x16x32_bf16 v[64:67], v[178:181], v[232:235], v[64:67]
	v_mfma_f32_16x16x32_bf16 v[68:71], v[158:161], v[232:235], v[68:71]
	v_mfma_f32_16x16x32_bf16 v[118:121], v[174:177], v[190:193], v[118:121]
	v_mfma_f32_16x16x32_bf16 v[114:117], v[182:185], v[190:193], v[114:117]
	v_mfma_f32_16x16x32_bf16 v[98:101], v[182:185], v[220:223], v[98:101]
	v_mfma_f32_16x16x32_bf16 v[102:105], v[174:177], v[220:223], v[102:105]
	v_mfma_f32_16x16x32_bf16 v[86:89], v[174:177], v[228:231], v[86:89]
	v_mfma_f32_16x16x32_bf16 v[82:85], v[182:185], v[228:231], v[82:85]
	v_mfma_f32_16x16x32_bf16 v[64:67], v[182:185], v[236:239], v[64:67]
	v_mfma_f32_16x16x32_bf16 v[68:71], v[174:177], v[236:239], v[68:71]
	s_setprio 0
	s_barrier
; #define PG8_STAGE(bufoff, gbase, voff) do { _Pragma("unroll") for (int _i = 0; _i < 2; ++_i) \
;         __builtin_amdgcn_global_load_lds((const unsigned*)((const char*)(gbase) + (voff)[_i]), (PG8_LAS unsigned*)(lds + (bufoff) + ldsw + _i * 8192), 16, 0, 0); } while (0)
; #define PG8_LDA(dst, b, h) do { _Pragma("unroll") for (int m = 0; m < 4; ++m) _Pragma("unroll") for (int k = 0; k < 2; ++k) dst[m][k] = *(const PG8_LAS bf16x8*)(lds + PG8_SA(b, h) + aoff + m * 2048 + k * 1024); } while (0)
; #define PG8_MMA(ai, bj, At, Bt) do { __builtin_amdgcn_s_setprio(1); _Pragma("unroll") for (int m = 0; m < 4; ++m) _Pragma("unroll") for (int n = 0; n < 2; ++n) _Pragma("unroll") for (int k = 0; k < 2; ++k) \
;         acc[ai][bj][m][n] = __builtin_amdgcn_mfma_f32_16x16x32_bf16(Bt[n][k], At[m][k], acc[ai][bj][m][n], 0, 0, 0); __builtin_amdgcn_s_setprio(0); } while (0)
; #define PG8_WAIT_V(n) asm volatile("s_waitcnt vmcnt(" #n ")" ::: "memory")
; #define PG8_WAIT_L(n) asm volatile("s_waitcnt lgkmcnt(" #n ")" ::: "memory")
; #define PG8_BAR __builtin_amdgcn_s_barrier()
;     __device__ __forceinline__ void operator()(const f32x4 (&acc)[2][2][4][2], const Unit& u, int wr, int wc, int fr_, int fq_, int) const {
;     ...
;         const bool lat = u.pm < 128; const int cond = lat ? (u.pm >> 5) : 4;
;         const float coef0 = (flags & 4) ? 1.0f : 0.5f;
;         const float* mv = modv + cond * E_MODW;
;         const size_t tb = lat ? (size_t)u.pm * BM * E_DM : (size_t)(u.pm - 128) * BM * E_DM;
;         const float* src = src_lat + tb; float* dst = (lat ? dst_lat : dst_ctx + (size_t)(u.kt0 >> 2) * (1024 * E_DM)) + tb;
;         const int col0 = u.pn * BM + wc * 32 + 4 * fq;
;         f32x4 g[2][2];
; #pragma unroll
;         for (int bj = 0; bj < 2; ++bj)
; #pragma unroll
;             for (int n = 0; n < 2; ++n) g[bj][n] = *(const f32x4*)(mv + col0 + bj * HALF + n * 16) * coef0;
; template <class Epi, class Sched, bool ALIGN_EPI = false, bool SP2 = false>
; __device__ __forceinline__ void gemm_phase(PG8_LAS unsigned char* lds, const Gemm g, const Sched& S, const Epi& E) {
;     ...
;             PG8_LDA(At, 1, 1); PG8_STAGE(PG8_SB(1, 0), b3, voffB); PG8_STAGE(PG8_SB(1, 1), b3 + hstep, voffB); PG8_STAGE(PG8_SA(1, 0), a3, voffA);
;             PG8_WAIT_V(8); PG8_WAIT_L(0); PG8_BAR; PG8_MMA(1, 0, At, B0); PG8_MMA(1, 1, At, B1); PG8_BAR; PG8_SCHED;
	s_add_i32 s42, s81, s16
	v_lshl_add_u64 v[194:195], v[194:195], 0, s[0:1]
	s_mov_b32 m0, s42
	ds_read_b128 v[186:189], v214 offset:49152
	ds_read_b128 v[190:193], v214 offset:50176
	ds_read_b128 v[216:219], v214 offset:51200
	ds_read_b128 v[220:223], v214 offset:52224
	ds_read_b128 v[224:227], v214 offset:53248
	ds_read_b128 v[228:231], v214 offset:54272
	ds_read_b128 v[232:235], v214 offset:55296
	ds_read_b128 v[236:239], v214 offset:56320
	global_load_lds_dwordx4 v[194:195], off
	v_lshl_add_u64 v[194:195], v[240:241], 0, s[0:1]
	s_add_i32 m0, s42, 0x2000
	s_add_i32 s42, s92, s16
	global_load_lds_dwordx4 v[194:195], off
	v_lshl_add_u64 v[194:195], v[242:243], 0, s[0:1]
	s_mov_b32 m0, s42
	s_nop 0
	global_load_lds_dwordx4 v[194:195], off
	v_lshl_add_u64 v[194:195], v[244:245], 0, s[0:1]
	s_add_i32 m0, s42, 0x2000
	s_nop 0
	global_load_lds_dwordx4 v[194:195], off
	v_lshl_add_u64 v[194:195], v[246:247], 0, s[0:1]
	s_mov_b32 m0, s8
	s_nop 0
	global_load_lds_dwordx4 v[194:195], off
	v_lshl_add_u64 v[194:195], v[248:249], 0, s[0:1]
	s_mov_b32 m0, s9
	s_nop 0
	global_load_lds_dwordx4 v[194:195], off
	s_waitcnt vmcnt(8)
	s_waitcnt lgkmcnt(0)
	s_barrier
	s_setprio 1
	s_waitcnt lgkmcnt(0)
	v_mfma_f32_16x16x32_bf16 v[60:63], v[130:133], v[186:189], v[60:63]
	v_mfma_f32_16x16x32_bf16 v[56:59], v[138:141], v[186:189], v[56:59]
	v_mfma_f32_16x16x32_bf16 v[40:43], v[138:141], v[216:219], v[40:43]
	v_mfma_f32_16x16x32_bf16 v[44:47], v[130:133], v[216:219], v[44:47]
	v_mfma_f32_16x16x32_bf16 v[28:31], v[130:133], v[224:227], v[28:31]
	v_mfma_f32_16x16x32_bf16 v[24:27], v[138:141], v[224:227], v[24:27]
	v_mfma_f32_16x16x32_bf16 v[8:11], v[138:141], v[232:235], v[8:11]
	v_mfma_f32_16x16x32_bf16 v[12:15], v[130:133], v[232:235], v[12:15]
	v_mfma_f32_16x16x32_bf16 v[60:63], v[134:137], v[190:193], v[60:63]
	v_mfma_f32_16x16x32_bf16 v[56:59], v[142:145], v[190:193], v[56:59]
	v_mfma_f32_16x16x32_bf16 v[40:43], v[142:145], v[220:223], v[40:43]
	v_mfma_f32_16x16x32_bf16 v[44:47], v[134:137], v[220:223], v[44:47]
	v_mfma_f32_16x16x32_bf16 v[28:31], v[134:137], v[228:231], v[28:31]
	v_mfma_f32_16x16x32_bf16 v[24:27], v[142:145], v[228:231], v[24:27]
	v_mfma_f32_16x16x32_bf16 v[8:11], v[142:145], v[236:239], v[8:11]
	v_mfma_f32_16x16x32_bf16 v[12:15], v[134:137], v[236:239], v[12:15]
	s_setprio 0
	s_setprio 1
	v_mfma_f32_16x16x32_bf16 v[52:55], v[158:161], v[186:189], v[52:55]
	v_mfma_f32_16x16x32_bf16 v[48:51], v[178:181], v[186:189], v[48:51]
	v_mfma_f32_16x16x32_bf16 v[32:35], v[178:181], v[216:219], v[32:35]
	v_mfma_f32_16x16x32_bf16 v[36:39], v[158:161], v[216:219], v[36:39]
	v_mfma_f32_16x16x32_bf16 v[20:23], v[158:161], v[224:227], v[20:23]
	v_mfma_f32_16x16x32_bf16 v[16:19], v[178:181], v[224:227], v[16:19]
	v_mfma_f32_16x16x32_bf16 v[0:3], v[178:181], v[232:235], v[0:3]
	v_mfma_f32_16x16x32_bf16 v[4:7], v[158:161], v[232:235], v[4:7]
	v_mfma_f32_16x16x32_bf16 v[52:55], v[174:177], v[190:193], v[52:55]
	v_mfma_f32_16x16x32_bf16 v[48:51], v[182:185], v[190:193], v[48:51]
	v_mfma_f32_16x16x32_bf16 v[32:35], v[182:185], v[220:223], v[32:35]
	v_mfma_f32_16x16x32_bf16 v[36:39], v[174:177], v[220:223], v[36:39]
	v_mfma_f32_16x16x32_bf16 v[20:23], v[174:177], v[228:231], v[20:23]
	v_mfma_f32_16x16x32_bf16 v[16:19], v[182:185], v[228:231], v[16:19]
	v_mfma_f32_16x16x32_bf16 v[0:3], v[182:185], v[236:239], v[0:3]
	v_mfma_f32_16x16x32_bf16 v[4:7], v[174:177], v[236:239], v[4:7]
	s_setprio 0
	s_barrier
	s_add_u32 s38, s38, 0x100
	s_addc_u32 s39, s39, 0
	s_add_u32 s41, s41, 0x100
	s_addc_u32 s45, s45, 0
	s_cmp_ge_u32 s71, s44
	s_mov_b32 s42, s71
	s_cbranch_scc0 .LBB0_647
	s_and_b64 vcc, exec, s[88:89]
	s_cbranch_vccz .LBB0_650
	s_barrier
.LBB0_650:
	s_cmpk_gt_i32 s14, 0x7f
	s_cselect_b64 s[44:45], -1, 0
	s_lshr_b32 s24, s14, 5
	s_cmpk_lt_i32 s14, 0x80
	s_cselect_b64 s[42:43], -1, 0
	s_mulk_i32 s24, 0x2400
	s_and_b64 s[38:39], s[42:43], exec
	s_cselect_b32 s38, s24, 0x9000
	s_ashr_i32 s39, s38, 31
	s_lshl_b64 s[92:93], s[38:39], 2
	s_add_u32 s38, s21, s92
	s_addc_u32 s39, s77, s93
	s_lshl_b32 s24, s13, 8
	v_mov_b32_e32 v188, v81
	v_mov_b32_e32 v215, v212
	s_or_b32 s24, s24, s66
	s_and_b64 s[94:95], s[74:75], s[42:43]
	v_lshl_add_u32 v186, v215, 2, s24
	v_ashrrev_i32_e32 v187, 31, v186
	v_lshl_add_u64 v[130:131], v[186:187], 2, s[38:39]
	global_load_dwordx4 v[142:145], v[130:131], off
	global_load_dwordx4 v[138:141], v[130:131], off offset:64
	global_load_dwordx4 v[134:137], v[130:131], off offset:512
	s_nop 0
	global_load_dwordx4 v[130:133], v[130:131], off offset:576
	v_cndmask_b32_e64 v151, 0, 1, s[94:95]
	v_cmp_ne_u32_e64 s[38:39], 1, v151
	s_andn2_b64 vcc, exec, s[94:95]
	s_cbranch_vccnz .LBB0_652
; __device__ __forceinline__ unsigned cvt_pk_bf16(float lo, float hi) { unsigned r; asm volatile("v_cvt_pk_bf16_f32 %0, %1, %2" : "=v"(r) : "v"(lo), "v"(hi)); return r; }
;     __device__ __forceinline__ void operator()(const f32x4 (&acc)[2][2][4][2], const Unit& u, int wr, int wc, int fr_, int fq_, int) const {
;     ...
;         const bool emit = lat && (flags & 1) != 0; bf16_t* XG = (flags & 2) ? XGb : XGa;
;         f32x4 gm[2][2];
;         if (emit) {
; #pragma unroll
;             for (int bj = 0; bj < 2; ++bj)
; #pragma unroll
;                 for (int n = 0; n < 2; ++n) gm[bj][n] = *(const f32x4*)(gnext + col0 + bj * HALF + n * 16) * (1.0f + *(const f32x4*)(sclnext + cond * E_MODW + col0 + bj * HALF + n * 16));
;         }
; #pragma unroll
;         for (int ai = 0; ai < 2; ++ai)
; #pragma unroll
;             for (int m = 0; m < 4; ++m) { const size_t off = (size_t)(ai * HALF + wr * 64 + m * 16 + fr) * E_DM + col0; float ss = 0.f;
; #pragma unroll
;                 for (int bj = 0; bj < 2; ++bj)
; #pragma unroll
;                     for (int n = 0; n < 2; ++n) {
;                         if (lat) { const f32x4 s = *(const f32x4*)(src + off + bj * HALF + n * 16);
;                             const f32x4 o = s + g[bj][n] * acc[ai][bj][m][n];
;                             *(f32x4*)(dst + off + bj * HALF + n * 16) = o;
;                             if (emit) { const f32x4 q = o * o; ss += (q[0] + q[1]) + (q[2] + q[3]); const f32x4 xg = o * gm[bj][n];
;                                 u32x2 w; w.x = cvt_pk_bf16(xg[0], xg[1]); w.y = cvt_pk_bf16(xg[2], xg[3]); *(u32x2*)(XG + tb + off + bj * HALF + n * 16) = w; } }
	v_lshrrev_b32_e32 v189, 2, v81
	v_and_b32_e32 v249, 3, v81
	v_lshl_add_u32 v189, v212, 2, v189
	v_lshl_add_u32 v186, v249, 2, s24
	s_add_u32 s38, s21, s92
	s_addc_u32 s39, s77, s93
	v_ashrrev_i32_e32 v187, 31, v186
	v_lshlrev_b64 v[158:159], 2, v[186:187]
	s_add_u32 s92, s10, s92
	s_addc_u32 s93, s48, s93
	v_lshl_add_u64 v[190:191], s[38:39], 0, v[158:159]
	global_load_dwordx4 v[142:145], v[190:191], off
	global_load_dwordx4 v[138:141], v[190:191], off offset:64
	global_load_dwordx4 v[134:137], v[190:191], off offset:512
	global_load_dwordx4 v[130:133], v[190:191], off offset:576
	v_lshl_add_u64 v[190:191], s[84:85], 0, v[158:159]
	v_lshl_add_u64 v[192:193], s[92:93], 0, v[158:159]
	global_load_dwordx4 v[182:185], v[190:191], off
	global_load_dwordx4 v[178:181], v[190:191], off offset:64
	global_load_dwordx4 v[174:177], v[190:191], off offset:576
	global_load_dwordx4 v[158:161], v[190:191], off offset:512
	global_load_dwordx4 v[232:235], v[192:193], off
	global_load_dwordx4 v[236:239], v[192:193], off offset:64
	global_load_dwordx4 v[240:243], v[192:193], off offset:512
	global_load_dwordx4 v[244:247], v[192:193], off offset:576
	s_lshl_b32 s40, s3, 6
	s_lshl_b32 s41, s63, 10
	s_add_i32 s40, s40, s41
	s_add_i32 s40, s40, 0x20000
	v_bfe_u32 v250, v81, 1, 2
	v_xor_b32_e32 v250, v250, v212
	v_lshlrev_b32_e32 v250, 4, v250
	v_lshl_add_u32 v250, v81, 6, v250
	v_add_u32_e32 v250, s40, v250
	v_bfe_u32 v251, v189, 1, 2
	v_xor_b32_e32 v251, v251, v249
	v_lshlrev_b32_e32 v251, 4, v251
	v_lshl_add_u32 v251, v189, 6, v251
	v_add_u32_e32 v251, s40, v251
	ds_write_b128 v250, v[126:129]
	ds_read_b128 v[126:129], v251
	ds_write_b128 v250, v[122:125]
	ds_read_b128 v[122:125], v251
	ds_write_b128 v250, v[118:121]
	ds_read_b128 v[118:121], v251
	ds_write_b128 v250, v[114:117]
	ds_read_b128 v[114:117], v251
	s_mov_b32 s94, s14
	s_ashr_i32 s95, s94, 31
	s_lshl_b64 s[96:97], s[94:95], 20
	v_readlane_b32 s24, v252, 47
	s_add_u32 s92, s24, s96
	v_readlane_b32 s24, v252, 46
	s_addc_u32 s93, s24, s97
	s_add_u32 s96, s56, s96
	s_addc_u32 s97, s57, s97
	s_lshl_b64 s[40:41], s[94:95], 19
	s_add_u32 s94, s2, s40
	s_addc_u32 s95, s46, s41
	v_add_u32_e32 v188, s3, v189
	v_ashrrev_i32_e32 v189, 31, v188
	v_lshlrev_b64 v[190:191], 10, v[188:189]
	v_lshl_add_u64 v[192:193], v[190:191], 0, v[186:187]
	v_lshlrev_b64 v[194:195], 2, v[192:193]
	v_lshl_add_u64 v[190:191], s[96:97], 0, v[194:195]
	v_lshl_add_u64 v[194:195], s[92:93], 0, v[194:195]
	v_lshl_add_u64 v[192:193], v[192:193], 1, s[94:95]
	global_load_dwordx4 v[216:219], v[194:195], off
	global_load_dwordx4 v[220:223], v[194:195], off offset:64
	global_load_dwordx4 v[224:227], v[194:195], off offset:512
	global_load_dwordx4 v[228:231], v[194:195], off offset:576
	s_mov_b32 s98, 0x8000
	s_mov_b32 s99, 0
	s_mov_b32 s96, 0x28000
	s_mov_b32 s97, 0
	v_mov_b32_e32 v151, v150
	s_waitcnt vmcnt(4)
	v_pk_add_f32 v[232:233], v[232:233], 1.0 op_sel_hi:[1,0]
	v_pk_add_f32 v[234:235], v[234:235], 1.0 op_sel_hi:[1,0]
	v_pk_add_f32 v[236:237], v[236:237], 1.0 op_sel_hi:[1,0]
	v_pk_add_f32 v[238:239], v[238:239], 1.0 op_sel_hi:[1,0]
	v_pk_add_f32 v[240:241], v[240:241], 1.0 op_sel_hi:[1,0]
	v_pk_add_f32 v[242:243], v[242:243], 1.0 op_sel_hi:[1,0]
	v_pk_add_f32 v[244:245], v[244:245], 1.0 op_sel_hi:[1,0]
	v_pk_add_f32 v[246:247], v[246:247], 1.0 op_sel_hi:[1,0]
	v_pk_mul_f32 v[182:183], v[182:183], v[232:233]
	v_pk_mul_f32 v[184:185], v[184:185], v[234:235]
	v_pk_mul_f32 v[178:179], v[178:179], v[236:237]
	v_pk_mul_f32 v[180:181], v[180:181], v[238:239]
	v_pk_mul_f32 v[158:159], v[158:159], v[240:241]
	v_pk_mul_f32 v[160:161], v[160:161], v[242:243]
	v_pk_mul_f32 v[174:175], v[174:175], v[244:245]
	v_pk_mul_f32 v[176:177], v[176:177], v[246:247]
	v_pk_mul_f32 v[142:143], v[150:151], v[142:143]
	v_pk_mul_f32 v[144:145], v[150:151], v[144:145]
	v_pk_mul_f32 v[138:139], v[150:151], v[138:139]
	v_pk_mul_f32 v[140:141], v[150:151], v[140:141]
	v_pk_mul_f32 v[134:135], v[150:151], v[134:135]
	v_pk_mul_f32 v[136:137], v[150:151], v[136:137]
	v_pk_mul_f32 v[130:131], v[150:151], v[130:131]
	v_pk_mul_f32 v[132:133], v[150:151], v[132:133]
	v_lshl_add_u64 v[194:195], s[98:99], 1, v[194:195]
	global_load_dwordx4 v[232:235], v[194:195], off
	global_load_dwordx4 v[236:239], v[194:195], off offset:64
	global_load_dwordx4 v[240:243], v[194:195], off offset:512
	global_load_dwordx4 v[244:247], v[194:195], off offset:576
	s_waitcnt lgkmcnt(0)
	ds_write_b128 v250, v[110:113]
	ds_read_b128 v[110:113], v251
	ds_write_b128 v250, v[106:109]
	ds_read_b128 v[106:109], v251
	ds_write_b128 v250, v[102:105]
	ds_read_b128 v[102:105], v251
	ds_write_b128 v250, v[98:101]
	ds_read_b128 v[98:101], v251
	s_waitcnt vmcnt(4)
; __device__ __forceinline__ unsigned cvt_pk_bf16(float lo, float hi) { unsigned r; asm volatile("v_cvt_pk_bf16_f32 %0, %1, %2" : "=v"(r) : "v"(lo), "v"(hi)); return r; }
;     __device__ __forceinline__ void operator()(const f32x4 (&acc)[2][2][4][2], const Unit& u, int wr, int wc, int fr_, int fq_, int) const {
;     ...
;             for (int m = 0; m < 4; ++m) { const size_t off = (size_t)(ai * HALF + wr * 64 + m * 16 + fr) * E_DM + col0; float ss = 0.f;
; #pragma unroll
;                 for (int bj = 0; bj < 2; ++bj)
; #pragma unroll
;                     for (int n = 0; n < 2; ++n) {
;                         if (lat) { const f32x4 s = *(const f32x4*)(src + off + bj * HALF + n * 16);
;                             const f32x4 o = s + g[bj][n] * acc[ai][bj][m][n];
;                             *(f32x4*)(dst + off + bj * HALF + n * 16) = o;
;                             if (emit) { const f32x4 q = o * o; ss += (q[0] + q[1]) + (q[2] + q[3]); const f32x4 xg = o * gm[bj][n];
;                                 u32x2 w; w.x = cvt_pk_bf16(xg[0], xg[1]); w.y = cvt_pk_bf16(xg[2], xg[3]); *(u32x2*)(XG + tb + off + bj * HALF + n * 16) = w; } }
	v_pk_fma_f32 v[128:129], v[128:129], v[144:145], v[218:219]
	v_pk_fma_f32 v[126:127], v[126:127], v[142:143], v[216:217]
	global_store_dwordx4 v[190:191], v[126:129], off
	v_pk_mul_f32 v[216:217], v[128:129], v[128:129]
	v_pk_mul_f32 v[218:219], v[126:127], v[126:127]
	v_pk_mul_f32 v[126:127], v[182:183], v[126:127]
	v_pk_mul_f32 v[128:129], v[184:185], v[128:129]
	v_add_f32_e32 v218, v218, v219
	v_add_f32_e32 v216, v216, v217
	v_add_f32_e32 v248, v218, v216
	v_cvt_pk_bf16_f32 v126, v126, v127
	v_cvt_pk_bf16_f32 v127, v128, v129
	global_store_dwordx2 v[192:193], v[126:127], off
	v_pk_fma_f32 v[124:125], v[124:125], v[140:141], v[222:223]
	v_pk_fma_f32 v[122:123], v[122:123], v[138:139], v[220:221]
	global_store_dwordx4 v[190:191], v[122:125], off offset:64
	v_pk_mul_f32 v[220:221], v[124:125], v[124:125]
	v_pk_mul_f32 v[222:223], v[122:123], v[122:123]
	v_pk_mul_f32 v[122:123], v[178:179], v[122:123]
	v_pk_mul_f32 v[124:125], v[180:181], v[124:125]
	v_add_f32_e32 v222, v222, v223
	v_add_f32_e32 v220, v220, v221
	v_add_f32_e32 v222, v222, v220
	v_add_f32_e32 v248, v248, v222
	v_cvt_pk_bf16_f32 v122, v122, v123
	v_cvt_pk_bf16_f32 v123, v124, v125
	global_store_dwordx2 v[192:193], v[122:123], off offset:32
	v_pk_fma_f32 v[120:121], v[120:121], v[136:137], v[226:227]
	v_pk_fma_f32 v[118:119], v[118:119], v[134:135], v[224:225]
	global_store_dwordx4 v[190:191], v[118:121], off offset:512
	v_pk_mul_f32 v[224:225], v[120:121], v[120:121]
	v_pk_mul_f32 v[226:227], v[118:119], v[118:119]
	v_pk_mul_f32 v[118:119], v[158:159], v[118:119]
	v_pk_mul_f32 v[120:121], v[160:161], v[120:121]
	v_add_f32_e32 v226, v226, v227
	v_add_f32_e32 v224, v224, v225
	v_add_f32_e32 v226, v226, v224
	v_add_f32_e32 v248, v248, v226
	v_cvt_pk_bf16_f32 v118, v118, v119
	v_cvt_pk_bf16_f32 v119, v120, v121
	global_store_dwordx2 v[192:193], v[118:119], off offset:256
	v_pk_fma_f32 v[116:117], v[116:117], v[132:133], v[230:231]
	v_pk_fma_f32 v[114:115], v[114:115], v[130:131], v[228:229]
	global_store_dwordx4 v[190:191], v[114:117], off offset:576
	v_pk_mul_f32 v[228:229], v[116:117], v[116:117]
	v_pk_mul_f32 v[230:231], v[114:115], v[114:115]
	v_pk_mul_f32 v[114:115], v[174:175], v[114:115]
	v_pk_mul_f32 v[116:117], v[176:177], v[116:117]
	v_add_f32_e32 v230, v230, v231
	v_add_f32_e32 v228, v228, v229
	v_add_f32_e32 v230, v230, v228
	v_add_f32_e32 v248, v248, v230
	v_cvt_pk_bf16_f32 v114, v114, v115
	v_cvt_pk_bf16_f32 v115, v116, v117
	global_store_dwordx2 v[192:193], v[114:115], off offset:288
	v_mov_b32_e32 v122, v248
	v_lshl_add_u64 v[190:191], s[98:99], 1, v[190:191]
	v_lshl_add_u64 v[192:193], s[98:99], 0, v[192:193]
	v_lshl_add_u64 v[194:195], s[98:99], 1, v[194:195]
	global_load_dwordx4 v[216:219], v[194:195], off
	global_load_dwordx4 v[220:223], v[194:195], off offset:64
	global_load_dwordx4 v[224:227], v[194:195], off offset:512
	global_load_dwordx4 v[228:231], v[194:195], off offset:576
	ds_write_b128 v250, v[94:97]
	ds_read_b128 v[94:97], v251
	ds_write_b128 v250, v[90:93]
	ds_read_b128 v[90:93], v251
	ds_write_b128 v250, v[86:89]
	ds_read_b128 v[86:89], v251
	ds_write_b128 v250, v[82:85]
	ds_read_b128 v[82:85], v251
	s_waitcnt vmcnt(12)
	s_waitcnt lgkmcnt(8)
	v_pk_fma_f32 v[112:113], v[112:113], v[144:145], v[234:235]
	v_pk_fma_f32 v[110:111], v[110:111], v[142:143], v[232:233]
	global_store_dwordx4 v[190:191], v[110:113], off
	v_pk_mul_f32 v[232:233], v[112:113], v[112:113]
	v_pk_mul_f32 v[234:235], v[110:111], v[110:111]
	v_pk_mul_f32 v[110:111], v[182:183], v[110:111]
	v_pk_mul_f32 v[112:113], v[184:185], v[112:113]
	v_add_f32_e32 v234, v234, v235
	v_add_f32_e32 v232, v232, v233
	v_add_f32_e32 v248, v234, v232
	v_cvt_pk_bf16_f32 v110, v110, v111
	v_cvt_pk_bf16_f32 v111, v112, v113
	global_store_dwordx2 v[192:193], v[110:111], off
	v_pk_fma_f32 v[108:109], v[108:109], v[140:141], v[238:239]
	v_pk_fma_f32 v[106:107], v[106:107], v[138:139], v[236:237]
	global_store_dwordx4 v[190:191], v[106:109], off offset:64
	v_pk_mul_f32 v[236:237], v[108:109], v[108:109]
	v_pk_mul_f32 v[238:239], v[106:107], v[106:107]
	v_pk_mul_f32 v[106:107], v[178:179], v[106:107]
	v_pk_mul_f32 v[108:109], v[180:181], v[108:109]
	v_add_f32_e32 v238, v238, v239
	v_add_f32_e32 v236, v236, v237
	v_add_f32_e32 v238, v238, v236
	v_add_f32_e32 v248, v248, v238
	v_cvt_pk_bf16_f32 v106, v106, v107
	v_cvt_pk_bf16_f32 v107, v108, v109
	global_store_dwordx2 v[192:193], v[106:107], off offset:32
	v_pk_fma_f32 v[104:105], v[104:105], v[136:137], v[242:243]
	v_pk_fma_f32 v[102:103], v[102:103], v[134:135], v[240:241]
	global_store_dwordx4 v[190:191], v[102:105], off offset:512
	v_pk_mul_f32 v[240:241], v[104:105], v[104:105]
	v_pk_mul_f32 v[242:243], v[102:103], v[102:103]
	v_pk_mul_f32 v[102:103], v[158:159], v[102:103]
	v_pk_mul_f32 v[104:105], v[160:161], v[104:105]
	v_add_f32_e32 v242, v242, v243
	v_add_f32_e32 v240, v240, v241
	v_add_f32_e32 v242, v242, v240
	v_add_f32_e32 v248, v248, v242
	v_cvt_pk_bf16_f32 v102, v102, v103
	v_cvt_pk_bf16_f32 v103, v104, v105
	global_store_dwordx2 v[192:193], v[102:103], off offset:256
	v_pk_fma_f32 v[100:101], v[100:101], v[132:133], v[246:247]
	v_pk_fma_f32 v[98:99], v[98:99], v[130:131], v[244:245]
	global_store_dwordx4 v[190:191], v[98:101], off offset:576
	v_pk_mul_f32 v[244:245], v[100:101], v[100:101]
	v_pk_mul_f32 v[246:247], v[98:99], v[98:99]
	v_pk_mul_f32 v[98:99], v[174:175], v[98:99]
	v_pk_mul_f32 v[100:101], v[176:177], v[100:101]
	v_add_f32_e32 v246, v246, v247
	v_add_f32_e32 v244, v244, v245
	v_add_f32_e32 v246, v246, v244
	v_add_f32_e32 v248, v248, v246
	v_cvt_pk_bf16_f32 v98, v98, v99
	v_cvt_pk_bf16_f32 v99, v100, v101
	global_store_dwordx2 v[192:193], v[98:99], off offset:288
	v_mov_b32_e32 v123, v248
	v_lshl_add_u64 v[190:191], s[98:99], 1, v[190:191]
	v_lshl_add_u64 v[192:193], s[98:99], 0, v[192:193]
	v_lshl_add_u64 v[194:195], s[98:99], 1, v[194:195]
	global_load_dwordx4 v[232:235], v[194:195], off
	global_load_dwordx4 v[236:239], v[194:195], off offset:64
	global_load_dwordx4 v[240:243], v[194:195], off offset:512
	global_load_dwordx4 v[244:247], v[194:195], off offset:576
	ds_write_b128 v250, v[76:79]
	ds_read_b128 v[76:79], v251
	ds_write_b128 v250, v[72:75]
	ds_read_b128 v[72:75], v251
	ds_write_b128 v250, v[68:71]
	ds_read_b128 v[68:71], v251
	ds_write_b128 v250, v[64:67]
	ds_read_b128 v[64:67], v251
	s_waitcnt vmcnt(12)
; __device__ __forceinline__ unsigned cvt_pk_bf16(float lo, float hi) { unsigned r; asm volatile("v_cvt_pk_bf16_f32 %0, %1, %2" : "=v"(r) : "v"(lo), "v"(hi)); return r; }
;     __device__ __forceinline__ void operator()(const f32x4 (&acc)[2][2][4][2], const Unit& u, int wr, int wc, int fr_, int fq_, int) const {
;     ...
;             for (int m = 0; m < 4; ++m) { const size_t off = (size_t)(ai * HALF + wr * 64 + m * 16 + fr) * E_DM + col0; float ss = 0.f;
; #pragma unroll
;                 for (int bj = 0; bj < 2; ++bj)
; #pragma unroll
;                     for (int n = 0; n < 2; ++n) {
;                         if (lat) { const f32x4 s = *(const f32x4*)(src + off + bj * HALF + n * 16);
;                             const f32x4 o = s + g[bj][n] * acc[ai][bj][m][n];
;                             *(f32x4*)(dst + off + bj * HALF + n * 16) = o;
;                             if (emit) { const f32x4 q = o * o; ss += (q[0] + q[1]) + (q[2] + q[3]); const f32x4 xg = o * gm[bj][n];
;                                 u32x2 w; w.x = cvt_pk_bf16(xg[0], xg[1]); w.y = cvt_pk_bf16(xg[2], xg[3]); *(u32x2*)(XG + tb + off + bj * HALF + n * 16) = w; } }
	s_waitcnt lgkmcnt(8)
	v_pk_fma_f32 v[96:97], v[96:97], v[144:145], v[218:219]
	v_pk_fma_f32 v[94:95], v[94:95], v[142:143], v[216:217]
	global_store_dwordx4 v[190:191], v[94:97], off
	v_pk_mul_f32 v[216:217], v[96:97], v[96:97]
	v_pk_mul_f32 v[218:219], v[94:95], v[94:95]
	v_pk_mul_f32 v[94:95], v[182:183], v[94:95]
	v_pk_mul_f32 v[96:97], v[184:185], v[96:97]
	v_add_f32_e32 v218, v218, v219
	v_add_f32_e32 v216, v216, v217
	v_add_f32_e32 v248, v218, v216
	v_cvt_pk_bf16_f32 v94, v94, v95
	v_cvt_pk_bf16_f32 v95, v96, v97
	global_store_dwordx2 v[192:193], v[94:95], off
	v_pk_fma_f32 v[92:93], v[92:93], v[140:141], v[222:223]
	v_pk_fma_f32 v[90:91], v[90:91], v[138:139], v[220:221]
	global_store_dwordx4 v[190:191], v[90:93], off offset:64
	v_pk_mul_f32 v[220:221], v[92:93], v[92:93]
	v_pk_mul_f32 v[222:223], v[90:91], v[90:91]
	v_pk_mul_f32 v[90:91], v[178:179], v[90:91]
	v_pk_mul_f32 v[92:93], v[180:181], v[92:93]
	v_add_f32_e32 v222, v222, v223
	v_add_f32_e32 v220, v220, v221
	v_add_f32_e32 v222, v222, v220
	v_add_f32_e32 v248, v248, v222
	v_cvt_pk_bf16_f32 v90, v90, v91
	v_cvt_pk_bf16_f32 v91, v92, v93
	global_store_dwordx2 v[192:193], v[90:91], off offset:32
	v_pk_fma_f32 v[88:89], v[88:89], v[136:137], v[226:227]
	v_pk_fma_f32 v[86:87], v[86:87], v[134:135], v[224:225]
	global_store_dwordx4 v[190:191], v[86:89], off offset:512
	v_pk_mul_f32 v[224:225], v[88:89], v[88:89]
	v_pk_mul_f32 v[226:227], v[86:87], v[86:87]
	v_pk_mul_f32 v[86:87], v[158:159], v[86:87]
	v_pk_mul_f32 v[88:89], v[160:161], v[88:89]
	v_add_f32_e32 v226, v226, v227
	v_add_f32_e32 v224, v224, v225
	v_add_f32_e32 v226, v226, v224
	v_add_f32_e32 v248, v248, v226
	v_cvt_pk_bf16_f32 v86, v86, v87
	v_cvt_pk_bf16_f32 v87, v88, v89
	global_store_dwordx2 v[192:193], v[86:87], off offset:256
	v_pk_fma_f32 v[84:85], v[84:85], v[132:133], v[230:231]
	v_pk_fma_f32 v[82:83], v[82:83], v[130:131], v[228:229]
	global_store_dwordx4 v[190:191], v[82:85], off offset:576
	v_pk_mul_f32 v[228:229], v[84:85], v[84:85]
	v_pk_mul_f32 v[230:231], v[82:83], v[82:83]
	v_pk_mul_f32 v[82:83], v[174:175], v[82:83]
	v_pk_mul_f32 v[84:85], v[176:177], v[84:85]
	v_add_f32_e32 v230, v230, v231
	v_add_f32_e32 v228, v228, v229
	v_add_f32_e32 v230, v230, v228
	v_add_f32_e32 v248, v248, v230
	v_cvt_pk_bf16_f32 v82, v82, v83
	v_cvt_pk_bf16_f32 v83, v84, v85
	global_store_dwordx2 v[192:193], v[82:83], off offset:288
	v_mov_b32_e32 v124, v248
	v_lshl_add_u64 v[190:191], s[98:99], 1, v[190:191]
	v_lshl_add_u64 v[192:193], s[98:99], 0, v[192:193]
	v_lshl_add_u64 v[194:195], s[96:97], 1, v[194:195]
	global_load_dwordx4 v[216:219], v[194:195], off
	global_load_dwordx4 v[220:223], v[194:195], off offset:64
	global_load_dwordx4 v[224:227], v[194:195], off offset:512
	global_load_dwordx4 v[228:231], v[194:195], off offset:576
	ds_write_b128 v250, v[60:63]
	ds_read_b128 v[60:63], v251
	ds_write_b128 v250, v[56:59]
	ds_read_b128 v[56:59], v251
	ds_write_b128 v250, v[52:55]
	ds_read_b128 v[52:55], v251
	ds_write_b128 v250, v[48:51]
	ds_read_b128 v[48:51], v251
	s_waitcnt vmcnt(12)
	s_waitcnt lgkmcnt(8)
	v_pk_fma_f32 v[78:79], v[78:79], v[144:145], v[234:235]
	v_pk_fma_f32 v[76:77], v[76:77], v[142:143], v[232:233]
	global_store_dwordx4 v[190:191], v[76:79], off
	v_pk_mul_f32 v[232:233], v[78:79], v[78:79]
	v_pk_mul_f32 v[234:235], v[76:77], v[76:77]
	v_pk_mul_f32 v[76:77], v[182:183], v[76:77]
	v_pk_mul_f32 v[78:79], v[184:185], v[78:79]
	v_add_f32_e32 v234, v234, v235
	v_add_f32_e32 v232, v232, v233
	v_add_f32_e32 v248, v234, v232
	v_cvt_pk_bf16_f32 v76, v76, v77
	v_cvt_pk_bf16_f32 v77, v78, v79
	global_store_dwordx2 v[192:193], v[76:77], off
	v_pk_fma_f32 v[74:75], v[74:75], v[140:141], v[238:239]
	v_pk_fma_f32 v[72:73], v[72:73], v[138:139], v[236:237]
	global_store_dwordx4 v[190:191], v[72:75], off offset:64
	v_pk_mul_f32 v[236:237], v[74:75], v[74:75]
	v_pk_mul_f32 v[238:239], v[72:73], v[72:73]
	v_pk_mul_f32 v[72:73], v[178:179], v[72:73]
	v_pk_mul_f32 v[74:75], v[180:181], v[74:75]
	v_add_f32_e32 v238, v238, v239
	v_add_f32_e32 v236, v236, v237
	v_add_f32_e32 v238, v238, v236
	v_add_f32_e32 v248, v248, v238
	v_cvt_pk_bf16_f32 v72, v72, v73
	v_cvt_pk_bf16_f32 v73, v74, v75
	global_store_dwordx2 v[192:193], v[72:73], off offset:32
	v_pk_fma_f32 v[70:71], v[70:71], v[136:137], v[242:243]
	v_pk_fma_f32 v[68:69], v[68:69], v[134:135], v[240:241]
	global_store_dwordx4 v[190:191], v[68:71], off offset:512
	v_pk_mul_f32 v[240:241], v[70:71], v[70:71]
	v_pk_mul_f32 v[242:243], v[68:69], v[68:69]
	v_pk_mul_f32 v[68:69], v[158:159], v[68:69]
	v_pk_mul_f32 v[70:71], v[160:161], v[70:71]
	v_add_f32_e32 v242, v242, v243
	v_add_f32_e32 v240, v240, v241
	v_add_f32_e32 v242, v242, v240
	v_add_f32_e32 v248, v248, v242
	v_cvt_pk_bf16_f32 v68, v68, v69
	v_cvt_pk_bf16_f32 v69, v70, v71
	global_store_dwordx2 v[192:193], v[68:69], off offset:256
	v_pk_fma_f32 v[66:67], v[66:67], v[132:133], v[246:247]
	v_pk_fma_f32 v[64:65], v[64:65], v[130:131], v[244:245]
	global_store_dwordx4 v[190:191], v[64:67], off offset:576
	v_pk_mul_f32 v[244:245], v[66:67], v[66:67]
	v_pk_mul_f32 v[246:247], v[64:65], v[64:65]
	v_pk_mul_f32 v[64:65], v[174:175], v[64:65]
	v_pk_mul_f32 v[66:67], v[176:177], v[66:67]
	v_add_f32_e32 v246, v246, v247
	v_add_f32_e32 v244, v244, v245
	v_add_f32_e32 v246, v246, v244
	v_add_f32_e32 v248, v248, v246
	v_cvt_pk_bf16_f32 v64, v64, v65
	v_cvt_pk_bf16_f32 v65, v66, v67
	global_store_dwordx2 v[192:193], v[64:65], off offset:288
	v_mov_b32_e32 v125, v248
	v_lshl_add_u64 v[190:191], s[96:97], 1, v[190:191]
	v_lshl_add_u64 v[192:193], s[96:97], 0, v[192:193]
	v_lshl_add_u64 v[194:195], s[98:99], 1, v[194:195]
	global_load_dwordx4 v[232:235], v[194:195], off
	global_load_dwordx4 v[236:239], v[194:195], off offset:64
	global_load_dwordx4 v[240:243], v[194:195], off offset:512
	global_load_dwordx4 v[244:247], v[194:195], off offset:576
	ds_write_b128 v250, v[44:47]
	ds_read_b128 v[44:47], v251
	ds_write_b128 v250, v[40:43]
	ds_read_b128 v[40:43], v251
	ds_write_b128 v250, v[36:39]
	ds_read_b128 v[36:39], v251
	ds_write_b128 v250, v[32:35]
	ds_read_b128 v[32:35], v251
	s_waitcnt vmcnt(12)
; __device__ __forceinline__ unsigned cvt_pk_bf16(float lo, float hi) { unsigned r; asm volatile("v_cvt_pk_bf16_f32 %0, %1, %2" : "=v"(r) : "v"(lo), "v"(hi)); return r; }
;     __device__ __forceinline__ void operator()(const f32x4 (&acc)[2][2][4][2], const Unit& u, int wr, int wc, int fr_, int fq_, int) const {
;     ...
;             for (int m = 0; m < 4; ++m) { const size_t off = (size_t)(ai * HALF + wr * 64 + m * 16 + fr) * E_DM + col0; float ss = 0.f;
; #pragma unroll
;                 for (int bj = 0; bj < 2; ++bj)
; #pragma unroll
;                     for (int n = 0; n < 2; ++n) {
;                         if (lat) { const f32x4 s = *(const f32x4*)(src + off + bj * HALF + n * 16);
;                             const f32x4 o = s + g[bj][n] * acc[ai][bj][m][n];
;                             *(f32x4*)(dst + off + bj * HALF + n * 16) = o;
;                             if (emit) { const f32x4 q = o * o; ss += (q[0] + q[1]) + (q[2] + q[3]); const f32x4 xg = o * gm[bj][n];
;                                 u32x2 w; w.x = cvt_pk_bf16(xg[0], xg[1]); w.y = cvt_pk_bf16(xg[2], xg[3]); *(u32x2*)(XG + tb + off + bj * HALF + n * 16) = w; } }
	s_waitcnt lgkmcnt(8)
	v_pk_fma_f32 v[62:63], v[62:63], v[144:145], v[218:219]
	v_pk_fma_f32 v[60:61], v[60:61], v[142:143], v[216:217]
	global_store_dwordx4 v[190:191], v[60:63], off
	v_pk_mul_f32 v[216:217], v[62:63], v[62:63]
	v_pk_mul_f32 v[218:219], v[60:61], v[60:61]
	v_pk_mul_f32 v[60:61], v[182:183], v[60:61]
	v_pk_mul_f32 v[62:63], v[184:185], v[62:63]
	v_add_f32_e32 v218, v218, v219
	v_add_f32_e32 v216, v216, v217
	v_add_f32_e32 v248, v218, v216
	v_cvt_pk_bf16_f32 v60, v60, v61
	v_cvt_pk_bf16_f32 v61, v62, v63
	global_store_dwordx2 v[192:193], v[60:61], off
	v_pk_fma_f32 v[58:59], v[58:59], v[140:141], v[222:223]
	v_pk_fma_f32 v[56:57], v[56:57], v[138:139], v[220:221]
	global_store_dwordx4 v[190:191], v[56:59], off offset:64
	v_pk_mul_f32 v[220:221], v[58:59], v[58:59]
	v_pk_mul_f32 v[222:223], v[56:57], v[56:57]
	v_pk_mul_f32 v[56:57], v[178:179], v[56:57]
	v_pk_mul_f32 v[58:59], v[180:181], v[58:59]
	v_add_f32_e32 v222, v222, v223
	v_add_f32_e32 v220, v220, v221
	v_add_f32_e32 v222, v222, v220
	v_add_f32_e32 v248, v248, v222
	v_cvt_pk_bf16_f32 v56, v56, v57
	v_cvt_pk_bf16_f32 v57, v58, v59
	global_store_dwordx2 v[192:193], v[56:57], off offset:32
	v_pk_fma_f32 v[54:55], v[54:55], v[136:137], v[226:227]
	v_pk_fma_f32 v[52:53], v[52:53], v[134:135], v[224:225]
	global_store_dwordx4 v[190:191], v[52:55], off offset:512
	v_pk_mul_f32 v[224:225], v[54:55], v[54:55]
	v_pk_mul_f32 v[226:227], v[52:53], v[52:53]
	v_pk_mul_f32 v[52:53], v[158:159], v[52:53]
	v_pk_mul_f32 v[54:55], v[160:161], v[54:55]
	v_add_f32_e32 v226, v226, v227
	v_add_f32_e32 v224, v224, v225
	v_add_f32_e32 v226, v226, v224
	v_add_f32_e32 v248, v248, v226
	v_cvt_pk_bf16_f32 v52, v52, v53
	v_cvt_pk_bf16_f32 v53, v54, v55
	global_store_dwordx2 v[192:193], v[52:53], off offset:256
	v_pk_fma_f32 v[50:51], v[50:51], v[132:133], v[230:231]
	v_pk_fma_f32 v[48:49], v[48:49], v[130:131], v[228:229]
	global_store_dwordx4 v[190:191], v[48:51], off offset:576
	v_pk_mul_f32 v[228:229], v[50:51], v[50:51]
	v_pk_mul_f32 v[230:231], v[48:49], v[48:49]
	v_pk_mul_f32 v[48:49], v[174:175], v[48:49]
	v_pk_mul_f32 v[50:51], v[176:177], v[50:51]
	v_add_f32_e32 v230, v230, v231
	v_add_f32_e32 v228, v228, v229
	v_add_f32_e32 v230, v230, v228
	v_add_f32_e32 v248, v248, v230
	v_cvt_pk_bf16_f32 v48, v48, v49
	v_cvt_pk_bf16_f32 v49, v50, v51
	global_store_dwordx2 v[192:193], v[48:49], off offset:288
	v_mov_b32_e32 v126, v248
	v_lshl_add_u64 v[190:191], s[98:99], 1, v[190:191]
	v_lshl_add_u64 v[192:193], s[98:99], 0, v[192:193]
	v_lshl_add_u64 v[194:195], s[98:99], 1, v[194:195]
	global_load_dwordx4 v[216:219], v[194:195], off
	global_load_dwordx4 v[220:223], v[194:195], off offset:64
	global_load_dwordx4 v[224:227], v[194:195], off offset:512
	global_load_dwordx4 v[228:231], v[194:195], off offset:576
	ds_write_b128 v250, v[28:31]
	ds_read_b128 v[28:31], v251
	ds_write_b128 v250, v[24:27]
	ds_read_b128 v[24:27], v251
	ds_write_b128 v250, v[20:23]
	ds_read_b128 v[20:23], v251
	ds_write_b128 v250, v[16:19]
	ds_read_b128 v[16:19], v251
	s_waitcnt vmcnt(12)
	s_waitcnt lgkmcnt(8)
	v_pk_fma_f32 v[46:47], v[46:47], v[144:145], v[234:235]
	v_pk_fma_f32 v[44:45], v[44:45], v[142:143], v[232:233]
	global_store_dwordx4 v[190:191], v[44:47], off
	v_pk_mul_f32 v[232:233], v[46:47], v[46:47]
	v_pk_mul_f32 v[234:235], v[44:45], v[44:45]
	v_pk_mul_f32 v[44:45], v[182:183], v[44:45]
	v_pk_mul_f32 v[46:47], v[184:185], v[46:47]
	v_add_f32_e32 v234, v234, v235
	v_add_f32_e32 v232, v232, v233
	v_add_f32_e32 v248, v234, v232
	v_cvt_pk_bf16_f32 v44, v44, v45
	v_cvt_pk_bf16_f32 v45, v46, v47
	global_store_dwordx2 v[192:193], v[44:45], off
	v_pk_fma_f32 v[42:43], v[42:43], v[140:141], v[238:239]
	v_pk_fma_f32 v[40:41], v[40:41], v[138:139], v[236:237]
	global_store_dwordx4 v[190:191], v[40:43], off offset:64
	v_pk_mul_f32 v[236:237], v[42:43], v[42:43]
	v_pk_mul_f32 v[238:239], v[40:41], v[40:41]
	v_pk_mul_f32 v[40:41], v[178:179], v[40:41]
	v_pk_mul_f32 v[42:43], v[180:181], v[42:43]
	v_add_f32_e32 v238, v238, v239
	v_add_f32_e32 v236, v236, v237
	v_add_f32_e32 v238, v238, v236
	v_add_f32_e32 v248, v248, v238
	v_cvt_pk_bf16_f32 v40, v40, v41
	v_cvt_pk_bf16_f32 v41, v42, v43
	global_store_dwordx2 v[192:193], v[40:41], off offset:32
	v_pk_fma_f32 v[38:39], v[38:39], v[136:137], v[242:243]
	v_pk_fma_f32 v[36:37], v[36:37], v[134:135], v[240:241]
	global_store_dwordx4 v[190:191], v[36:39], off offset:512
	v_pk_mul_f32 v[240:241], v[38:39], v[38:39]
	v_pk_mul_f32 v[242:243], v[36:37], v[36:37]
	v_pk_mul_f32 v[36:37], v[158:159], v[36:37]
	v_pk_mul_f32 v[38:39], v[160:161], v[38:39]
	v_add_f32_e32 v242, v242, v243
	v_add_f32_e32 v240, v240, v241
	v_add_f32_e32 v242, v242, v240
	v_add_f32_e32 v248, v248, v242
	v_cvt_pk_bf16_f32 v36, v36, v37
	v_cvt_pk_bf16_f32 v37, v38, v39
	global_store_dwordx2 v[192:193], v[36:37], off offset:256
	v_pk_fma_f32 v[34:35], v[34:35], v[132:133], v[246:247]
	v_pk_fma_f32 v[32:33], v[32:33], v[130:131], v[244:245]
	global_store_dwordx4 v[190:191], v[32:35], off offset:576
	v_pk_mul_f32 v[244:245], v[34:35], v[34:35]
	v_pk_mul_f32 v[246:247], v[32:33], v[32:33]
	v_pk_mul_f32 v[32:33], v[174:175], v[32:33]
	v_pk_mul_f32 v[34:35], v[176:177], v[34:35]
	v_add_f32_e32 v246, v246, v247
	v_add_f32_e32 v244, v244, v245
	v_add_f32_e32 v246, v246, v244
	v_add_f32_e32 v248, v248, v246
	v_cvt_pk_bf16_f32 v32, v32, v33
	v_cvt_pk_bf16_f32 v33, v34, v35
	global_store_dwordx2 v[192:193], v[32:33], off offset:288
	v_mov_b32_e32 v127, v248
	v_lshl_add_u64 v[190:191], s[98:99], 1, v[190:191]
	v_lshl_add_u64 v[192:193], s[98:99], 0, v[192:193]
	v_lshl_add_u64 v[194:195], s[98:99], 1, v[194:195]
	global_load_dwordx4 v[232:235], v[194:195], off
	global_load_dwordx4 v[236:239], v[194:195], off offset:64
	global_load_dwordx4 v[240:243], v[194:195], off offset:512
	global_load_dwordx4 v[244:247], v[194:195], off offset:576
	ds_write_b128 v250, v[12:15]
	ds_read_b128 v[12:15], v251
	ds_write_b128 v250, v[8:11]
	ds_read_b128 v[8:11], v251
	ds_write_b128 v250, v[4:7]
	ds_read_b128 v[4:7], v251
	ds_write_b128 v250, v[0:3]
	ds_read_b128 v[0:3], v251
	s_waitcnt vmcnt(12)
; __device__ __forceinline__ unsigned cvt_pk_bf16(float lo, float hi) { unsigned r; asm volatile("v_cvt_pk_bf16_f32 %0, %1, %2" : "=v"(r) : "v"(lo), "v"(hi)); return r; }
;     __device__ __forceinline__ void operator()(const f32x4 (&acc)[2][2][4][2], const Unit& u, int wr, int wc, int fr_, int fq_, int) const {
;     ...
;             for (int m = 0; m < 4; ++m) { const size_t off = (size_t)(ai * HALF + wr * 64 + m * 16 + fr) * E_DM + col0; float ss = 0.f;
; #pragma unroll
;                 for (int bj = 0; bj < 2; ++bj)
; #pragma unroll
;                     for (int n = 0; n < 2; ++n) {
;                         if (lat) { const f32x4 s = *(const f32x4*)(src + off + bj * HALF + n * 16);
;                             const f32x4 o = s + g[bj][n] * acc[ai][bj][m][n];
;                             *(f32x4*)(dst + off + bj * HALF + n * 16) = o;
;                             if (emit) { const f32x4 q = o * o; ss += (q[0] + q[1]) + (q[2] + q[3]); const f32x4 xg = o * gm[bj][n];
;                                 u32x2 w; w.x = cvt_pk_bf16(xg[0], xg[1]); w.y = cvt_pk_bf16(xg[2], xg[3]); *(u32x2*)(XG + tb + off + bj * HALF + n * 16) = w; } }
	s_waitcnt lgkmcnt(8)
	v_pk_fma_f32 v[30:31], v[30:31], v[144:145], v[218:219]
	v_pk_fma_f32 v[28:29], v[28:29], v[142:143], v[216:217]
	global_store_dwordx4 v[190:191], v[28:31], off
	v_pk_mul_f32 v[216:217], v[30:31], v[30:31]
	v_pk_mul_f32 v[218:219], v[28:29], v[28:29]
	v_pk_mul_f32 v[28:29], v[182:183], v[28:29]
	v_pk_mul_f32 v[30:31], v[184:185], v[30:31]
	v_add_f32_e32 v218, v218, v219
	v_add_f32_e32 v216, v216, v217
	v_add_f32_e32 v248, v218, v216
	v_cvt_pk_bf16_f32 v28, v28, v29
	v_cvt_pk_bf16_f32 v29, v30, v31
	global_store_dwordx2 v[192:193], v[28:29], off
	v_pk_fma_f32 v[26:27], v[26:27], v[140:141], v[222:223]
	v_pk_fma_f32 v[24:25], v[24:25], v[138:139], v[220:221]
	global_store_dwordx4 v[190:191], v[24:27], off offset:64
	v_pk_mul_f32 v[220:221], v[26:27], v[26:27]
	v_pk_mul_f32 v[222:223], v[24:25], v[24:25]
	v_pk_mul_f32 v[24:25], v[178:179], v[24:25]
	v_pk_mul_f32 v[26:27], v[180:181], v[26:27]
	v_add_f32_e32 v222, v222, v223
	v_add_f32_e32 v220, v220, v221
	v_add_f32_e32 v222, v222, v220
	v_add_f32_e32 v248, v248, v222
	v_cvt_pk_bf16_f32 v24, v24, v25
	v_cvt_pk_bf16_f32 v25, v26, v27
	global_store_dwordx2 v[192:193], v[24:25], off offset:32
	v_pk_fma_f32 v[22:23], v[22:23], v[136:137], v[226:227]
	v_pk_fma_f32 v[20:21], v[20:21], v[134:135], v[224:225]
	global_store_dwordx4 v[190:191], v[20:23], off offset:512
	v_pk_mul_f32 v[224:225], v[22:23], v[22:23]
	v_pk_mul_f32 v[226:227], v[20:21], v[20:21]
	v_pk_mul_f32 v[20:21], v[158:159], v[20:21]
	v_pk_mul_f32 v[22:23], v[160:161], v[22:23]
	v_add_f32_e32 v226, v226, v227
	v_add_f32_e32 v224, v224, v225
	v_add_f32_e32 v226, v226, v224
	v_add_f32_e32 v248, v248, v226
	v_cvt_pk_bf16_f32 v20, v20, v21
	v_cvt_pk_bf16_f32 v21, v22, v23
	global_store_dwordx2 v[192:193], v[20:21], off offset:256
	v_pk_fma_f32 v[18:19], v[18:19], v[132:133], v[230:231]
	v_pk_fma_f32 v[16:17], v[16:17], v[130:131], v[228:229]
	global_store_dwordx4 v[190:191], v[16:19], off offset:576
	v_pk_mul_f32 v[228:229], v[18:19], v[18:19]
	v_pk_mul_f32 v[230:231], v[16:17], v[16:17]
	v_pk_mul_f32 v[16:17], v[174:175], v[16:17]
	v_pk_mul_f32 v[18:19], v[176:177], v[18:19]
	v_add_f32_e32 v230, v230, v231
	v_add_f32_e32 v228, v228, v229
	v_add_f32_e32 v230, v230, v228
	v_add_f32_e32 v248, v248, v230
	v_cvt_pk_bf16_f32 v16, v16, v17
	v_cvt_pk_bf16_f32 v17, v18, v19
	global_store_dwordx2 v[192:193], v[16:17], off offset:288
	v_mov_b32_e32 v128, v248
	v_lshl_add_u64 v[190:191], s[98:99], 1, v[190:191]
	v_lshl_add_u64 v[192:193], s[98:99], 0, v[192:193]
	s_waitcnt vmcnt(8)
	s_waitcnt lgkmcnt(0)
; __device__ __forceinline__ unsigned cvt_pk_bf16(float lo, float hi) { unsigned r; asm volatile("v_cvt_pk_bf16_f32 %0, %1, %2" : "=v"(r) : "v"(lo), "v"(hi)); return r; }
;     __device__ __forceinline__ void operator()(const f32x4 (&acc)[2][2][4][2], const Unit& u, int wr, int wc, int fr_, int fq_, int) const {
;     ...
;                             if (emit) { const f32x4 q = o * o; ss += (q[0] + q[1]) + (q[2] + q[3]); const f32x4 xg = o * gm[bj][n];
;                                 u32x2 w; w.x = cvt_pk_bf16(xg[0], xg[1]); w.y = cvt_pk_bf16(xg[2], xg[3]); *(u32x2*)(XG + tb + off + bj * HALF + n * 16) = w; } }
;                         else *(f32x4*)(dst + off + bj * HALF + n * 16) = g[bj][n] * acc[ai][bj][m][n];
;                     }
;                 if (emit) { ss += __shfl_xor(ss, 16); ss += __shfl_xor(ss, 32); if (fq == 0) SS[(size_t)(u.pm * BM + ai * HALF + wr * 64 + m * 16 + fr) * 16 + u.pn * 4 + wc] = ss; }
	v_pk_fma_f32 v[14:15], v[14:15], v[144:145], v[234:235]
	v_pk_fma_f32 v[12:13], v[12:13], v[142:143], v[232:233]
	global_store_dwordx4 v[190:191], v[12:15], off
	v_pk_mul_f32 v[232:233], v[14:15], v[14:15]
	v_pk_mul_f32 v[234:235], v[12:13], v[12:13]
	v_pk_mul_f32 v[12:13], v[182:183], v[12:13]
	v_pk_mul_f32 v[14:15], v[184:185], v[14:15]
	v_add_f32_e32 v234, v234, v235
	v_add_f32_e32 v232, v232, v233
	v_add_f32_e32 v248, v234, v232
	v_cvt_pk_bf16_f32 v12, v12, v13
	v_cvt_pk_bf16_f32 v13, v14, v15
	global_store_dwordx2 v[192:193], v[12:13], off
	v_pk_fma_f32 v[10:11], v[10:11], v[140:141], v[238:239]
	v_pk_fma_f32 v[8:9], v[8:9], v[138:139], v[236:237]
	global_store_dwordx4 v[190:191], v[8:11], off offset:64
	v_pk_mul_f32 v[236:237], v[10:11], v[10:11]
	v_pk_mul_f32 v[238:239], v[8:9], v[8:9]
	v_pk_mul_f32 v[8:9], v[178:179], v[8:9]
	v_pk_mul_f32 v[10:11], v[180:181], v[10:11]
	v_add_f32_e32 v238, v238, v239
	v_add_f32_e32 v236, v236, v237
	v_add_f32_e32 v238, v238, v236
	v_add_f32_e32 v248, v248, v238
	v_cvt_pk_bf16_f32 v8, v8, v9
	v_cvt_pk_bf16_f32 v9, v10, v11
	global_store_dwordx2 v[192:193], v[8:9], off offset:32
	v_pk_fma_f32 v[6:7], v[6:7], v[136:137], v[242:243]
	v_pk_fma_f32 v[4:5], v[4:5], v[134:135], v[240:241]
	global_store_dwordx4 v[190:191], v[4:7], off offset:512
	v_pk_mul_f32 v[240:241], v[6:7], v[6:7]
	v_pk_mul_f32 v[242:243], v[4:5], v[4:5]
	v_pk_mul_f32 v[4:5], v[158:159], v[4:5]
	v_pk_mul_f32 v[6:7], v[160:161], v[6:7]
	v_add_f32_e32 v242, v242, v243
	v_add_f32_e32 v240, v240, v241
	v_add_f32_e32 v242, v242, v240
	v_add_f32_e32 v248, v248, v242
	v_cvt_pk_bf16_f32 v4, v4, v5
	v_cvt_pk_bf16_f32 v5, v6, v7
	global_store_dwordx2 v[192:193], v[4:5], off offset:256
	v_pk_fma_f32 v[2:3], v[2:3], v[132:133], v[246:247]
	v_pk_fma_f32 v[0:1], v[0:1], v[130:131], v[244:245]
	global_store_dwordx4 v[190:191], v[0:3], off offset:576
	v_pk_mul_f32 v[244:245], v[2:3], v[2:3]
	v_pk_mul_f32 v[246:247], v[0:1], v[0:1]
	v_pk_mul_f32 v[0:1], v[174:175], v[0:1]
	v_pk_mul_f32 v[2:3], v[176:177], v[2:3]
	v_add_f32_e32 v246, v246, v247
	v_add_f32_e32 v244, v244, v245
	v_add_f32_e32 v246, v246, v244
	v_add_f32_e32 v248, v248, v246
	v_cvt_pk_bf16_f32 v0, v0, v1
	v_cvt_pk_bf16_f32 v1, v2, v3
	global_store_dwordx2 v[192:193], v[0:1], off offset:288
	v_mov_b32_e32 v129, v248
	v_readlane_b32 s80, v252, 0
	v_readlane_b32 s81, v252, 1
	v_readlane_b32 s82, v254, 59
	v_lshl_add_u32 v250, s14, 8, v188
	v_ashrrev_i32_e32 v251, 31, v250
	v_lshlrev_b64 v[250:251], 6, v[250:251]
	s_lshl_b32 s98, s13, 2
	s_ashr_i32 s99, s98, 31
	v_lshl_add_u64 v[250:251], s[80:81], 0, v[250:251]
	v_lshl_add_u64 v[250:251], s[98:99], 2, v[250:251]
	s_lshl_b32 s24, s63, 2
	v_lshl_add_u64 v[250:251], v[250:251], 0, s[24:25]
	v_and_b32_e32 v249, 3, v81
	v_add_f32_dpp v122, v122, v122 quad_perm:[1,0,3,2] row_mask:0xf bank_mask:0xf
	v_add_f32_dpp v123, v123, v123 quad_perm:[1,0,3,2] row_mask:0xf bank_mask:0xf
	v_add_f32_dpp v124, v124, v124 quad_perm:[1,0,3,2] row_mask:0xf bank_mask:0xf
	v_add_f32_dpp v125, v125, v125 quad_perm:[1,0,3,2] row_mask:0xf bank_mask:0xf
	v_add_f32_dpp v126, v126, v126 quad_perm:[1,0,3,2] row_mask:0xf bank_mask:0xf
	v_add_f32_dpp v127, v127, v127 quad_perm:[1,0,3,2] row_mask:0xf bank_mask:0xf
	v_add_f32_dpp v128, v128, v128 quad_perm:[1,0,3,2] row_mask:0xf bank_mask:0xf
	v_add_f32_dpp v129, v129, v129 quad_perm:[1,0,3,2] row_mask:0xf bank_mask:0xf
	v_cmp_eq_u32_e64 s[44:45], 0, v249
	v_add_f32_dpp v122, v122, v122 quad_perm:[2,3,0,1] row_mask:0xf bank_mask:0xf
	v_add_f32_dpp v123, v123, v123 quad_perm:[2,3,0,1] row_mask:0xf bank_mask:0xf
	v_add_f32_dpp v124, v124, v124 quad_perm:[2,3,0,1] row_mask:0xf bank_mask:0xf
	v_add_f32_dpp v125, v125, v125 quad_perm:[2,3,0,1] row_mask:0xf bank_mask:0xf
	v_add_f32_dpp v126, v126, v126 quad_perm:[2,3,0,1] row_mask:0xf bank_mask:0xf
	v_add_f32_dpp v127, v127, v127 quad_perm:[2,3,0,1] row_mask:0xf bank_mask:0xf
	v_add_f32_dpp v128, v128, v128 quad_perm:[2,3,0,1] row_mask:0xf bank_mask:0xf
	v_add_f32_dpp v129, v129, v129 quad_perm:[2,3,0,1] row_mask:0xf bank_mask:0xf
	s_mov_b32 s98, 0x2000
	s_mov_b32 s99, 0
	s_and_saveexec_b64 s[38:39], s[44:45]
	global_store_dword v[250:251], v122, off
	global_store_dword v[250:251], v123, off offset:1024
	global_store_dword v[250:251], v124, off offset:2048
	global_store_dword v[250:251], v125, off offset:3072
	v_lshl_add_u64 v[250:251], s[98:99], 0, v[250:251]
	global_store_dword v[250:251], v126, off
	global_store_dword v[250:251], v127, off offset:1024
	global_store_dword v[250:251], v128, off offset:2048
	global_store_dword v[250:251], v129, off offset:3072
	s_or_b64 exec, exec, s[38:39]
	s_branch .LBB0_844
